# v16 + mid-block s_setprio 0/1 pair removed in the GEMM K-loops (one priority raise per 32-MFMA block)
# speedup vs baseline: 1.0075x; 1.0075x over previous
; #define PG8_STAGE(bufoff, gbase, voff) do { _Pragma("unroll") for (int _i = 0; _i < 2; ++_i) \
;         __builtin_amdgcn_global_load_lds((const unsigned*)((const char*)(gbase) + (voff)[_i]), (PG8_LAS unsigned*)(lds + (bufoff) + ldsw + _i * 8192), 16, 0, 0); } while (0)
; #define PG8_LDA(dst, b, h) do { _Pragma("unroll") for (int m = 0; m < 4; ++m) _Pragma("unroll") for (int k = 0; k < 2; ++k) dst[m][k] = *(const PG8_LAS bf16x8*)(lds + PG8_SA(b, h) + aoff + m * 2048 + k * 1024); } while (0)
; #define PG8_LDB(dst, b, h) do { _Pragma("unroll") for (int n = 0; n < 2; ++n) _Pragma("unroll") for (int k = 0; k < 2; ++k) dst[n][k] = *(const PG8_LAS bf16x8*)(lds + PG8_SB(b, h) + boff + n * 2048 + k * 1024); } while (0)
; #define PG8_MMA(ai, bj, At, Bt) do { __builtin_amdgcn_s_setprio(1); _Pragma("unroll") for (int m = 0; m < 4; ++m) _Pragma("unroll") for (int n = 0; n < 2; ++n) _Pragma("unroll") for (int k = 0; k < 2; ++k) \
;         acc[ai][bj][m][n] = __builtin_amdgcn_mfma_f32_16x16x32_bf16(Bt[n][k], At[m][k], acc[ai][bj][m][n], 0, 0, 0); __builtin_amdgcn_s_setprio(0); } while (0)
; #define PG8_WAIT_V(n) asm volatile("s_waitcnt vmcnt(" #n ")" ::: "memory")
; #define PG8_WAIT_L(n) asm volatile("s_waitcnt lgkmcnt(" #n ")" ::: "memory")
; #define PG8_BAR __builtin_amdgcn_s_barrier()
; #define PG8_SCHED __builtin_amdgcn_sched_barrier(0)
; template <class Epi, class Sched, bool ALIGN_EPI = false, bool SP2 = false>
; __device__ __forceinline__ void gemm_phase(PG8_LAS unsigned char* lds, const Gemm g, const Sched& S, const Epi& E) {
;     ...
;             PG8_LDB(B0, 0, 0); PG8_LDB(B1, 0, 1); PG8_SCHED; PG8_LDA(At, 0, 0); PG8_STAGE(PG8_SA(1, 1), a1 + hstep, voffA);
;             PG8_WAIT_V(8); PG8_WAIT_L(0); PG8_BAR; PG8_MMA(0, 0, At, B0); PG8_MMA(0, 1, At, B1); PG8_BAR; PG8_SCHED;
;             PG8_LDA(At, 0, 1); PG8_STAGE(PG8_SB(0, 0), b2, voffB); PG8_STAGE(PG8_SB(0, 1), b2 + hstepB, voffB); PG8_STAGE(PG8_SA(0, 0), a2, voffA);
;             PG8_WAIT_V(8); PG8_WAIT_L(0); PG8_BAR; PG8_MMA(1, 0, At, B0); PG8_MMA(1, 1, At, B1); PG8_BAR; PG8_SCHED;
.LBB0_192:
	ds_read_b128 v[146:149], v152
	ds_read_b128 v[156:159], v152 offset:1024
	ds_read_b128 v[160:163], v152 offset:2048
	ds_read_b128 v[164:167], v152 offset:3072
	ds_read_b128 v[168:171], v153
	ds_read_b128 v[172:175], v153 offset:1024
	ds_read_b128 v[176:179], v153 offset:2048
	ds_read_b128 v[180:183], v153 offset:3072
	s_add_u32 s22, s20, 0xfffc0080
	s_addc_u32 s23, s21, -1
	s_cmp_eq_u32 s75, 12
	s_cselect_b32 s25, s5, s23
	s_cselect_b32 s24, s13, s22
	s_cselect_b32 s23, s11, s74
	s_cselect_b32 s22, s19, s73
	v_lshl_add_u64 v[216:217], s[20:21], 0, v[138:139]
	s_add_i32 m0, s27, 0xc000
	ds_read_b128 v[184:187], v154
	ds_read_b128 v[188:191], v154 offset:1024
	ds_read_b128 v[192:195], v154 offset:2048
	ds_read_b128 v[196:199], v154 offset:3072
	ds_read_b128 v[200:203], v154 offset:4096
	ds_read_b128 v[204:207], v154 offset:5120
	ds_read_b128 v[208:211], v154 offset:6144
	ds_read_b128 v[212:215], v154 offset:7168
	global_load_lds_dwordx4 v[216:217], off
	v_lshl_add_u64 v[216:217], s[20:21], 0, v[140:141]
	s_add_i32 m0, s27, 0xe000
	s_nop 0
	global_load_lds_dwordx4 v[216:217], off
	s_waitcnt vmcnt(8)
	s_waitcnt lgkmcnt(0)
	s_barrier
	s_setprio 1
	s_waitcnt lgkmcnt(0)
	v_mfma_f32_16x16x32_bf16 v[126:129], v[146:149], v[184:187], v[126:129]
	v_mfma_f32_16x16x32_bf16 v[122:125], v[160:163], v[184:187], v[122:125]
	v_mfma_f32_16x16x32_bf16 v[114:117], v[146:149], v[192:195], v[114:117]
	v_mfma_f32_16x16x32_bf16 v[106:109], v[160:163], v[192:195], v[106:109]
	v_mfma_f32_16x16x32_bf16 v[98:101], v[146:149], v[200:203], v[98:101]
	v_mfma_f32_16x16x32_bf16 v[90:93], v[160:163], v[200:203], v[90:93]
	v_mfma_f32_16x16x32_bf16 v[82:85], v[146:149], v[208:211], v[82:85]
	v_mfma_f32_16x16x32_bf16 v[74:77], v[160:163], v[208:211], v[74:77]
	v_mfma_f32_16x16x32_bf16 v[126:129], v[156:159], v[188:191], v[126:129]
	v_mfma_f32_16x16x32_bf16 v[122:125], v[164:167], v[188:191], v[122:125]
	v_mfma_f32_16x16x32_bf16 v[114:117], v[156:159], v[196:199], v[114:117]
	v_mfma_f32_16x16x32_bf16 v[106:109], v[164:167], v[196:199], v[106:109]
	v_mfma_f32_16x16x32_bf16 v[98:101], v[156:159], v[204:207], v[98:101]
	v_mfma_f32_16x16x32_bf16 v[90:93], v[164:167], v[204:207], v[90:93]
	v_mfma_f32_16x16x32_bf16 v[82:85], v[156:159], v[212:215], v[82:85]
	v_mfma_f32_16x16x32_bf16 v[74:77], v[164:167], v[212:215], v[74:77]
	v_mfma_f32_16x16x32_bf16 v[118:121], v[168:171], v[184:187], v[118:121]
	v_mfma_f32_16x16x32_bf16 v[110:113], v[176:179], v[184:187], v[110:113]
	v_mfma_f32_16x16x32_bf16 v[102:105], v[168:171], v[192:195], v[102:105]
	v_mfma_f32_16x16x32_bf16 v[94:97], v[176:179], v[192:195], v[94:97]
	v_mfma_f32_16x16x32_bf16 v[86:89], v[168:171], v[200:203], v[86:89]
	v_mfma_f32_16x16x32_bf16 v[78:81], v[176:179], v[200:203], v[78:81]
	v_mfma_f32_16x16x32_bf16 v[70:73], v[168:171], v[208:211], v[70:73]
	v_mfma_f32_16x16x32_bf16 v[66:69], v[176:179], v[208:211], v[66:69]
	v_mfma_f32_16x16x32_bf16 v[118:121], v[172:175], v[188:191], v[118:121]
	v_mfma_f32_16x16x32_bf16 v[110:113], v[180:183], v[188:191], v[110:113]
	v_mfma_f32_16x16x32_bf16 v[102:105], v[172:175], v[196:199], v[102:105]
	v_mfma_f32_16x16x32_bf16 v[94:97], v[180:183], v[196:199], v[94:97]
	v_mfma_f32_16x16x32_bf16 v[86:89], v[172:175], v[204:207], v[86:89]
	v_mfma_f32_16x16x32_bf16 v[78:81], v[180:183], v[204:207], v[78:81]
	v_mfma_f32_16x16x32_bf16 v[70:73], v[172:175], v[212:215], v[70:73]
	v_mfma_f32_16x16x32_bf16 v[66:69], v[180:183], v[212:215], v[66:69]
	s_setprio 0
	s_barrier
	s_add_i32 s76, s69, s26
	v_lshl_add_u64 v[216:217], s[22:23], 0, v[132:133]
	s_mov_b32 m0, s76
	ds_read_b128 v[184:187], v154 offset:16384
	ds_read_b128 v[188:191], v154 offset:17408
	ds_read_b128 v[192:195], v154 offset:18432
	ds_read_b128 v[196:199], v154 offset:19456
	ds_read_b128 v[200:203], v154 offset:20480
	ds_read_b128 v[204:207], v154 offset:21504
	ds_read_b128 v[208:211], v154 offset:22528
	ds_read_b128 v[212:215], v154 offset:23552
	global_load_lds_dwordx4 v[216:217], off
	s_add_i32 m0, s76, 0x2000
	s_add_u32 s76, s22, 0x10000
	v_lshl_add_u64 v[218:219], s[22:23], 0, v[136:137]
	s_addc_u32 s77, s23, 0
	s_add_i32 s78, s70, s26
	global_load_lds_dwordx4 v[218:219], off
	v_lshl_add_u64 v[220:221], s[76:77], 0, v[132:133]
	s_mov_b32 m0, s78
	v_lshl_add_u64 v[222:223], s[24:25], 0, v[134:135]
	global_load_lds_dwordx4 v[220:221], off
	v_lshl_add_u64 v[220:221], s[76:77], 0, v[136:137]
	s_add_i32 m0, s78, 0x2000
	s_nop 0
	global_load_lds_dwordx4 v[220:221], off
	v_lshl_add_u64 v[220:221], s[24:25], 0, v[130:131]
	s_mov_b32 m0, s27
	s_nop 0
	global_load_lds_dwordx4 v[220:221], off
	s_mov_b32 m0, s28
	s_nop 0
	global_load_lds_dwordx4 v[222:223], off
	s_waitcnt vmcnt(8)
	s_waitcnt lgkmcnt(0)
	s_barrier
; #define PG8_STAGE(bufoff, gbase, voff) do { _Pragma("unroll") for (int _i = 0; _i < 2; ++_i) \
;         __builtin_amdgcn_global_load_lds((const unsigned*)((const char*)(gbase) + (voff)[_i]), (PG8_LAS unsigned*)(lds + (bufoff) + ldsw + _i * 8192), 16, 0, 0); } while (0)
; #define PG8_LDA(dst, b, h) do { _Pragma("unroll") for (int m = 0; m < 4; ++m) _Pragma("unroll") for (int k = 0; k < 2; ++k) dst[m][k] = *(const PG8_LAS bf16x8*)(lds + PG8_SA(b, h) + aoff + m * 2048 + k * 1024); } while (0)
; #define PG8_LDB(dst, b, h) do { _Pragma("unroll") for (int n = 0; n < 2; ++n) _Pragma("unroll") for (int k = 0; k < 2; ++k) dst[n][k] = *(const PG8_LAS bf16x8*)(lds + PG8_SB(b, h) + boff + n * 2048 + k * 1024); } while (0)
; #define PG8_MMA(ai, bj, At, Bt) do { __builtin_amdgcn_s_setprio(1); _Pragma("unroll") for (int m = 0; m < 4; ++m) _Pragma("unroll") for (int n = 0; n < 2; ++n) _Pragma("unroll") for (int k = 0; k < 2; ++k) \
;         acc[ai][bj][m][n] = __builtin_amdgcn_mfma_f32_16x16x32_bf16(Bt[n][k], At[m][k], acc[ai][bj][m][n], 0, 0, 0); __builtin_amdgcn_s_setprio(0); } while (0)
; #define PG8_WAIT_V(n) asm volatile("s_waitcnt vmcnt(" #n ")" ::: "memory")
; #define PG8_WAIT_L(n) asm volatile("s_waitcnt lgkmcnt(" #n ")" ::: "memory")
; #define PG8_BAR __builtin_amdgcn_s_barrier()
; #define PG8_SCHED __builtin_amdgcn_sched_barrier(0)
; template <class Epi, class Sched, bool ALIGN_EPI = false, bool SP2 = false>
; __device__ __forceinline__ void gemm_phase(PG8_LAS unsigned char* lds, const Gemm g, const Sched& S, const Epi& E) {
;     ...
;             PG8_WAIT_V(8); PG8_WAIT_L(0); PG8_BAR; PG8_MMA(1, 0, At, B0); PG8_MMA(1, 1, At, B1); PG8_BAR; PG8_SCHED;
;             PG8_LDB(B0, 1, 0); PG8_LDB(B1, 1, 1); PG8_SCHED; PG8_LDA(At, 1, 0); PG8_STAGE(PG8_SA(0, 1), a2 + hstep, voffA);
;             PG8_WAIT_V(8); PG8_WAIT_L(0); PG8_BAR; PG8_MMA(0, 0, At, B0); PG8_MMA(0, 1, At, B1); PG8_BAR; PG8_SCHED;
	s_setprio 1
	s_waitcnt lgkmcnt(0)
	v_mfma_f32_16x16x32_bf16 v[62:65], v[146:149], v[184:187], v[62:65]
	v_mfma_f32_16x16x32_bf16 v[58:61], v[160:163], v[184:187], v[58:61]
	v_mfma_f32_16x16x32_bf16 v[50:53], v[146:149], v[192:195], v[50:53]
	v_mfma_f32_16x16x32_bf16 v[42:45], v[160:163], v[192:195], v[42:45]
	v_mfma_f32_16x16x32_bf16 v[34:37], v[146:149], v[200:203], v[34:37]
	v_mfma_f32_16x16x32_bf16 v[26:29], v[160:163], v[200:203], v[26:29]
	v_mfma_f32_16x16x32_bf16 v[18:21], v[146:149], v[208:211], v[18:21]
	v_mfma_f32_16x16x32_bf16 v[10:13], v[160:163], v[208:211], v[10:13]
	v_mfma_f32_16x16x32_bf16 v[62:65], v[156:159], v[188:191], v[62:65]
	v_mfma_f32_16x16x32_bf16 v[58:61], v[164:167], v[188:191], v[58:61]
	v_mfma_f32_16x16x32_bf16 v[50:53], v[156:159], v[196:199], v[50:53]
	v_mfma_f32_16x16x32_bf16 v[42:45], v[164:167], v[196:199], v[42:45]
	v_mfma_f32_16x16x32_bf16 v[34:37], v[156:159], v[204:207], v[34:37]
	v_mfma_f32_16x16x32_bf16 v[26:29], v[164:167], v[204:207], v[26:29]
	v_mfma_f32_16x16x32_bf16 v[18:21], v[156:159], v[212:215], v[18:21]
	v_mfma_f32_16x16x32_bf16 v[10:13], v[164:167], v[212:215], v[10:13]
	v_mfma_f32_16x16x32_bf16 v[54:57], v[168:171], v[184:187], v[54:57]
	v_mfma_f32_16x16x32_bf16 v[46:49], v[176:179], v[184:187], v[46:49]
	v_mfma_f32_16x16x32_bf16 v[38:41], v[168:171], v[192:195], v[38:41]
	v_mfma_f32_16x16x32_bf16 v[30:33], v[176:179], v[192:195], v[30:33]
	v_mfma_f32_16x16x32_bf16 v[22:25], v[168:171], v[200:203], v[22:25]
	v_mfma_f32_16x16x32_bf16 v[14:17], v[176:179], v[200:203], v[14:17]
	v_mfma_f32_16x16x32_bf16 v[6:9], v[168:171], v[208:211], v[6:9]
	v_mfma_f32_16x16x32_bf16 v[2:5], v[176:179], v[208:211], v[2:5]
	v_mfma_f32_16x16x32_bf16 v[54:57], v[172:175], v[188:191], v[54:57]
	v_mfma_f32_16x16x32_bf16 v[46:49], v[180:183], v[188:191], v[46:49]
	v_mfma_f32_16x16x32_bf16 v[38:41], v[172:175], v[196:199], v[38:41]
	v_mfma_f32_16x16x32_bf16 v[30:33], v[180:183], v[196:199], v[30:33]
	v_mfma_f32_16x16x32_bf16 v[22:25], v[172:175], v[204:207], v[22:25]
	v_mfma_f32_16x16x32_bf16 v[14:17], v[180:183], v[204:207], v[14:17]
	v_mfma_f32_16x16x32_bf16 v[6:9], v[172:175], v[212:215], v[6:9]
	v_mfma_f32_16x16x32_bf16 v[2:5], v[180:183], v[212:215], v[2:5]
	s_setprio 0
	s_barrier
	s_add_i32 s76, 0, 0x18000
	v_add_u32_e32 v155, s76, v150
	s_add_i32 s77, 0, 0x1c000
	ds_read_b128 v[146:149], v155
	ds_read_b128 v[156:159], v155 offset:1024
	ds_read_b128 v[160:163], v155 offset:2048
	ds_read_b128 v[164:167], v155 offset:3072
	v_add_u32_e32 v155, s77, v150
	ds_read_b128 v[168:171], v155
	ds_read_b128 v[172:175], v155 offset:1024
	ds_read_b128 v[176:179], v155 offset:2048
	ds_read_b128 v[180:183], v155 offset:3072
	s_add_u32 s24, s24, 0x40000
	s_addc_u32 s25, s25, 0
	s_mov_b32 m0, s29
	v_lshl_add_u64 v[224:225], s[24:25], 0, v[130:131]
	ds_read_b128 v[184:187], v154 offset:32768
	ds_read_b128 v[188:191], v154 offset:33792
	ds_read_b128 v[192:195], v154 offset:34816
	ds_read_b128 v[196:199], v154 offset:35840
	ds_read_b128 v[200:203], v154 offset:36864
	ds_read_b128 v[204:207], v154 offset:37888
	ds_read_b128 v[208:211], v154 offset:38912
	ds_read_b128 v[212:215], v154 offset:39936
	global_load_lds_dwordx4 v[224:225], off
	v_lshl_add_u64 v[224:225], s[24:25], 0, v[134:135]
	s_mov_b32 m0, s30
	s_nop 0
	global_load_lds_dwordx4 v[224:225], off
	s_waitcnt vmcnt(8)
	s_waitcnt lgkmcnt(0)
	s_barrier
	s_setprio 1
	s_waitcnt lgkmcnt(0)
	v_mfma_f32_16x16x32_bf16 v[126:129], v[146:149], v[184:187], v[126:129]
	v_mfma_f32_16x16x32_bf16 v[122:125], v[160:163], v[184:187], v[122:125]
	v_mfma_f32_16x16x32_bf16 v[114:117], v[146:149], v[192:195], v[114:117]
	v_mfma_f32_16x16x32_bf16 v[106:109], v[160:163], v[192:195], v[106:109]
	v_mfma_f32_16x16x32_bf16 v[98:101], v[146:149], v[200:203], v[98:101]
	v_mfma_f32_16x16x32_bf16 v[90:93], v[160:163], v[200:203], v[90:93]
	v_mfma_f32_16x16x32_bf16 v[82:85], v[146:149], v[208:211], v[82:85]
	v_mfma_f32_16x16x32_bf16 v[74:77], v[160:163], v[208:211], v[74:77]
	v_mfma_f32_16x16x32_bf16 v[126:129], v[156:159], v[188:191], v[126:129]
	v_mfma_f32_16x16x32_bf16 v[122:125], v[164:167], v[188:191], v[122:125]
	v_mfma_f32_16x16x32_bf16 v[114:117], v[156:159], v[196:199], v[114:117]
	v_mfma_f32_16x16x32_bf16 v[106:109], v[164:167], v[196:199], v[106:109]
	v_mfma_f32_16x16x32_bf16 v[98:101], v[156:159], v[204:207], v[98:101]
	v_mfma_f32_16x16x32_bf16 v[90:93], v[164:167], v[204:207], v[90:93]
	v_mfma_f32_16x16x32_bf16 v[82:85], v[156:159], v[212:215], v[82:85]
	v_mfma_f32_16x16x32_bf16 v[74:77], v[164:167], v[212:215], v[74:77]
	v_mfma_f32_16x16x32_bf16 v[118:121], v[168:171], v[184:187], v[118:121]
	v_mfma_f32_16x16x32_bf16 v[110:113], v[176:179], v[184:187], v[110:113]
	v_mfma_f32_16x16x32_bf16 v[102:105], v[168:171], v[192:195], v[102:105]
	v_mfma_f32_16x16x32_bf16 v[94:97], v[176:179], v[192:195], v[94:97]
	v_mfma_f32_16x16x32_bf16 v[86:89], v[168:171], v[200:203], v[86:89]
	v_mfma_f32_16x16x32_bf16 v[78:81], v[176:179], v[200:203], v[78:81]
	v_mfma_f32_16x16x32_bf16 v[70:73], v[168:171], v[208:211], v[70:73]
	v_mfma_f32_16x16x32_bf16 v[66:69], v[176:179], v[208:211], v[66:69]
	v_mfma_f32_16x16x32_bf16 v[118:121], v[172:175], v[188:191], v[118:121]
	v_mfma_f32_16x16x32_bf16 v[110:113], v[180:183], v[188:191], v[110:113]
	v_mfma_f32_16x16x32_bf16 v[102:105], v[172:175], v[196:199], v[102:105]
	v_mfma_f32_16x16x32_bf16 v[94:97], v[180:183], v[196:199], v[94:97]
	v_mfma_f32_16x16x32_bf16 v[86:89], v[172:175], v[204:207], v[86:89]
	v_mfma_f32_16x16x32_bf16 v[78:81], v[180:183], v[204:207], v[78:81]
	v_mfma_f32_16x16x32_bf16 v[70:73], v[172:175], v[212:215], v[70:73]
	v_mfma_f32_16x16x32_bf16 v[66:69], v[180:183], v[212:215], v[66:69]
	s_setprio 0
	s_barrier
; #define PG8_STAGE(bufoff, gbase, voff) do { _Pragma("unroll") for (int _i = 0; _i < 2; ++_i) \
;         __builtin_amdgcn_global_load_lds((const unsigned*)((const char*)(gbase) + (voff)[_i]), (PG8_LAS unsigned*)(lds + (bufoff) + ldsw + _i * 8192), 16, 0, 0); } while (0)
; #define PG8_LDA(dst, b, h) do { _Pragma("unroll") for (int m = 0; m < 4; ++m) _Pragma("unroll") for (int k = 0; k < 2; ++k) dst[m][k] = *(const PG8_LAS bf16x8*)(lds + PG8_SA(b, h) + aoff + m * 2048 + k * 1024); } while (0)
; #define PG8_MMA(ai, bj, At, Bt) do { __builtin_amdgcn_s_setprio(1); _Pragma("unroll") for (int m = 0; m < 4; ++m) _Pragma("unroll") for (int n = 0; n < 2; ++n) _Pragma("unroll") for (int k = 0; k < 2; ++k) \
;         acc[ai][bj][m][n] = __builtin_amdgcn_mfma_f32_16x16x32_bf16(Bt[n][k], At[m][k], acc[ai][bj][m][n], 0, 0, 0); __builtin_amdgcn_s_setprio(0); } while (0)
; #define PG8_WAIT_V(n) asm volatile("s_waitcnt vmcnt(" #n ")" ::: "memory")
; #define PG8_WAIT_L(n) asm volatile("s_waitcnt lgkmcnt(" #n ")" ::: "memory")
; #define PG8_BAR __builtin_amdgcn_s_barrier()
; #define PG8_SCHED __builtin_amdgcn_sched_barrier(0)
; template <class Epi, class Sched, bool ALIGN_EPI = false, bool SP2 = false>
; __device__ __forceinline__ void gemm_phase(PG8_LAS unsigned char* lds, const Gemm g, const Sched& S, const Epi& E) {
;     ...
;             PG8_LDA(At, 1, 1); PG8_STAGE(PG8_SB(1, 0), b3, voffB); PG8_STAGE(PG8_SB(1, 1), b3 + hstepB, voffB); PG8_STAGE(PG8_SA(1, 0), a3, voffA);
;             PG8_WAIT_V(8); PG8_WAIT_L(0); PG8_BAR; PG8_MMA(1, 0, At, B0); PG8_MMA(1, 1, At, B1); PG8_BAR; PG8_SCHED;
	s_add_i32 s24, s76, s26
	v_lshl_add_u64 v[216:217], v[216:217], 0, s[6:7]
	s_mov_b32 m0, s24
	ds_read_b128 v[184:187], v154 offset:49152
	ds_read_b128 v[188:191], v154 offset:50176
	ds_read_b128 v[192:195], v154 offset:51200
	ds_read_b128 v[196:199], v154 offset:52224
	ds_read_b128 v[200:203], v154 offset:53248
	ds_read_b128 v[204:207], v154 offset:54272
	ds_read_b128 v[208:211], v154 offset:55296
	ds_read_b128 v[212:215], v154 offset:56320
	global_load_lds_dwordx4 v[216:217], off
	s_add_i32 m0, s24, 0x2000
	s_add_u32 s22, s22, 0x10080
	v_lshl_add_u64 v[216:217], v[218:219], 0, s[6:7]
	s_addc_u32 s23, s23, 0
	s_add_i32 s24, s77, s26
	global_load_lds_dwordx4 v[216:217], off
	v_lshl_add_u64 v[216:217], s[22:23], 0, v[132:133]
	s_mov_b32 m0, s24
	s_nop 0
	global_load_lds_dwordx4 v[216:217], off
	v_lshl_add_u64 v[216:217], s[22:23], 0, v[136:137]
	s_add_i32 m0, s24, 0x2000
	s_nop 0
	global_load_lds_dwordx4 v[216:217], off
	v_lshl_add_u64 v[216:217], v[220:221], 0, s[6:7]
	s_mov_b32 m0, s33
	s_nop 0
	global_load_lds_dwordx4 v[216:217], off
	v_lshl_add_u64 v[216:217], v[222:223], 0, s[6:7]
	s_mov_b32 m0, s34
	s_nop 0
	global_load_lds_dwordx4 v[216:217], off
	s_waitcnt vmcnt(8)
	s_waitcnt lgkmcnt(0)
	s_barrier
	s_setprio 1
	s_waitcnt lgkmcnt(0)
	v_mfma_f32_16x16x32_bf16 v[62:65], v[146:149], v[184:187], v[62:65]
	v_mfma_f32_16x16x32_bf16 v[58:61], v[160:163], v[184:187], v[58:61]
	v_mfma_f32_16x16x32_bf16 v[50:53], v[146:149], v[192:195], v[50:53]
	v_mfma_f32_16x16x32_bf16 v[42:45], v[160:163], v[192:195], v[42:45]
	v_mfma_f32_16x16x32_bf16 v[34:37], v[146:149], v[200:203], v[34:37]
	v_mfma_f32_16x16x32_bf16 v[26:29], v[160:163], v[200:203], v[26:29]
	v_mfma_f32_16x16x32_bf16 v[18:21], v[146:149], v[208:211], v[18:21]
	v_mfma_f32_16x16x32_bf16 v[10:13], v[160:163], v[208:211], v[10:13]
	v_mfma_f32_16x16x32_bf16 v[62:65], v[156:159], v[188:191], v[62:65]
	v_mfma_f32_16x16x32_bf16 v[58:61], v[164:167], v[188:191], v[58:61]
	v_mfma_f32_16x16x32_bf16 v[50:53], v[156:159], v[196:199], v[50:53]
	v_mfma_f32_16x16x32_bf16 v[42:45], v[164:167], v[196:199], v[42:45]
	v_mfma_f32_16x16x32_bf16 v[34:37], v[156:159], v[204:207], v[34:37]
	v_mfma_f32_16x16x32_bf16 v[26:29], v[164:167], v[204:207], v[26:29]
	v_mfma_f32_16x16x32_bf16 v[18:21], v[156:159], v[212:215], v[18:21]
	v_mfma_f32_16x16x32_bf16 v[10:13], v[164:167], v[212:215], v[10:13]
	v_mfma_f32_16x16x32_bf16 v[54:57], v[168:171], v[184:187], v[54:57]
	v_mfma_f32_16x16x32_bf16 v[46:49], v[176:179], v[184:187], v[46:49]
	v_mfma_f32_16x16x32_bf16 v[38:41], v[168:171], v[192:195], v[38:41]
	v_mfma_f32_16x16x32_bf16 v[30:33], v[176:179], v[192:195], v[30:33]
	v_mfma_f32_16x16x32_bf16 v[22:25], v[168:171], v[200:203], v[22:25]
	v_mfma_f32_16x16x32_bf16 v[14:17], v[176:179], v[200:203], v[14:17]
	v_mfma_f32_16x16x32_bf16 v[6:9], v[168:171], v[208:211], v[6:9]
	v_mfma_f32_16x16x32_bf16 v[2:5], v[176:179], v[208:211], v[2:5]
	v_mfma_f32_16x16x32_bf16 v[54:57], v[172:175], v[188:191], v[54:57]
	v_mfma_f32_16x16x32_bf16 v[46:49], v[180:183], v[188:191], v[46:49]
	v_mfma_f32_16x16x32_bf16 v[38:41], v[172:175], v[196:199], v[38:41]
	v_mfma_f32_16x16x32_bf16 v[30:33], v[180:183], v[196:199], v[30:33]
	v_mfma_f32_16x16x32_bf16 v[22:25], v[172:175], v[204:207], v[22:25]
	v_mfma_f32_16x16x32_bf16 v[14:17], v[180:183], v[204:207], v[14:17]
	v_mfma_f32_16x16x32_bf16 v[6:9], v[172:175], v[212:215], v[6:9]
	v_mfma_f32_16x16x32_bf16 v[2:5], v[180:183], v[212:215], v[2:5]
	s_setprio 0
	s_barrier
	s_add_i32 s75, s75, 2
	s_add_u32 s20, s20, 0x100
	s_addc_u32 s21, s21, 0
	s_add_u32 s73, s73, 0x100
	s_addc_u32 s74, s74, 0
	s_cmp_gt_u32 s75, 13
	s_cbranch_scc0 .LBB0_192
	s_and_b64 vcc, exec, s[8:9]
	s_cbranch_vccz .LBB0_195
	s_barrier

; #define PG8_STAGE(bufoff, gbase, voff) do { _Pragma("unroll") for (int _i = 0; _i < 2; ++_i) \
;         __builtin_amdgcn_global_load_lds((const unsigned*)((const char*)(gbase) + (voff)[_i]), (PG8_LAS unsigned*)(lds + (bufoff) + ldsw + _i * 8192), 16, 0, 0); } while (0)
; #define PG8_LDA(dst, b, h) do { _Pragma("unroll") for (int m = 0; m < 4; ++m) _Pragma("unroll") for (int k = 0; k < 2; ++k) dst[m][k] = *(const PG8_LAS bf16x8*)(lds + PG8_SA(b, h) + aoff + m * 2048 + k * 1024); } while (0)
; #define PG8_LDB(dst, b, h) do { _Pragma("unroll") for (int n = 0; n < 2; ++n) _Pragma("unroll") for (int k = 0; k < 2; ++k) dst[n][k] = *(const PG8_LAS bf16x8*)(lds + PG8_SB(b, h) + boff + n * 2048 + k * 1024); } while (0)
; #define PG8_MMA(ai, bj, At, Bt) do { __builtin_amdgcn_s_setprio(1); _Pragma("unroll") for (int m = 0; m < 4; ++m) _Pragma("unroll") for (int n = 0; n < 2; ++n) _Pragma("unroll") for (int k = 0; k < 2; ++k) \
;         acc[ai][bj][m][n] = __builtin_amdgcn_mfma_f32_16x16x32_bf16(Bt[n][k], At[m][k], acc[ai][bj][m][n], 0, 0, 0); __builtin_amdgcn_s_setprio(0); } while (0)
; #define PG8_WAIT_V(n) asm volatile("s_waitcnt vmcnt(" #n ")" ::: "memory")
; #define PG8_WAIT_L(n) asm volatile("s_waitcnt lgkmcnt(" #n ")" ::: "memory")
; #define PG8_BAR __builtin_amdgcn_s_barrier()
; #define PG8_SCHED __builtin_amdgcn_sched_barrier(0)
; template <class Epi, class Sched, bool ALIGN_EPI = false, bool SP2 = false>
; __device__ __forceinline__ void gemm_phase(PG8_LAS unsigned char* lds, const Gemm g, const Sched& S, const Epi& E) {
;     ...
;             PG8_LDB(B0, 0, 0); PG8_LDB(B1, 0, 1); PG8_SCHED; PG8_LDA(At, 0, 0); PG8_STAGE(PG8_SA(1, 1), a1 + hstep, voffA);
;             PG8_WAIT_V(8); PG8_WAIT_L(0); PG8_BAR; PG8_MMA(0, 0, At, B0); PG8_MMA(0, 1, At, B1); PG8_BAR; PG8_SCHED;
;             PG8_LDA(At, 0, 1); PG8_STAGE(PG8_SB(0, 0), b2, voffB); PG8_STAGE(PG8_SB(0, 1), b2 + hstepB, voffB); PG8_STAGE(PG8_SA(0, 0), a2, voffA);
;             PG8_WAIT_V(8); PG8_WAIT_L(0); PG8_BAR; PG8_MMA(1, 0, At, B0); PG8_MMA(1, 1, At, B1); PG8_BAR; PG8_SCHED;
.LBB0_1094:
	v_add_u32_e32 v3, s46, v224
	ds_read_b128 v[134:137], v3
	ds_read_b128 v[138:141], v3 offset:1024
	ds_read_b128 v[142:145], v3 offset:2048
	ds_read_b128 v[146:149], v3 offset:3072
	v_add_u32_e32 v3, s47, v224
	s_add_u32 s26, s22, s24
	ds_read_b128 v[150:153], v3
	ds_read_b128 v[154:157], v3 offset:1024
	ds_read_b128 v[158:161], v3 offset:2048
	ds_read_b128 v[162:165], v3 offset:3072
	s_addc_u32 s27, s23, s25
	s_add_u32 s26, s26, 0x100
	s_addc_u32 s27, s27, 0
	s_add_u32 s58, s62, s24
	s_addc_u32 s59, s63, s25
	s_cmpk_eq_i32 s24, 0x700
	s_cselect_b32 s29, s17, s27
	s_cselect_b32 s28, s54, s26
	s_cselect_b32 s27, s56, s59
	s_cselect_b32 s26, s57, s58
	v_lshl_add_u64 v[4:5], v[214:215], 0, s[24:25]
	s_add_i32 m0, s33, 0xc000
	ds_read_b128 v[166:169], v226
	ds_read_b128 v[170:173], v226 offset:1024
	ds_read_b128 v[174:177], v226 offset:2048
	ds_read_b128 v[178:181], v226 offset:3072
	ds_read_b128 v[182:185], v226 offset:4096
	ds_read_b128 v[186:189], v226 offset:5120
	ds_read_b128 v[190:193], v226 offset:6144
	ds_read_b128 v[194:197], v226 offset:7168
	global_load_lds_dwordx4 v[4:5], off
	v_lshl_add_u64 v[4:5], v[216:217], 0, s[24:25]
	s_add_i32 m0, s33, 0xe000
	s_nop 0
	global_load_lds_dwordx4 v[4:5], off
	s_waitcnt vmcnt(8)
	s_waitcnt lgkmcnt(0)
	s_barrier
	s_setprio 1
	s_waitcnt lgkmcnt(0)
	v_mfma_f32_16x16x32_bf16 v[130:133], v[134:137], v[166:169], v[130:133]
	v_mfma_f32_16x16x32_bf16 v[126:129], v[142:145], v[166:169], v[126:129]
	v_mfma_f32_16x16x32_bf16 v[114:117], v[134:137], v[174:177], v[114:117]
	v_mfma_f32_16x16x32_bf16 v[110:113], v[142:145], v[174:177], v[110:113]
	v_mfma_f32_16x16x32_bf16 v[98:101], v[134:137], v[182:185], v[98:101]
	v_mfma_f32_16x16x32_bf16 v[94:97], v[142:145], v[182:185], v[94:97]
	v_mfma_f32_16x16x32_bf16 v[82:85], v[134:137], v[190:193], v[82:85]
	v_mfma_f32_16x16x32_bf16 v[78:81], v[142:145], v[190:193], v[78:81]
	v_mfma_f32_16x16x32_bf16 v[130:133], v[138:141], v[170:173], v[130:133]
	v_mfma_f32_16x16x32_bf16 v[126:129], v[146:149], v[170:173], v[126:129]
	v_mfma_f32_16x16x32_bf16 v[114:117], v[138:141], v[178:181], v[114:117]
	v_mfma_f32_16x16x32_bf16 v[110:113], v[146:149], v[178:181], v[110:113]
	v_mfma_f32_16x16x32_bf16 v[98:101], v[138:141], v[186:189], v[98:101]
	v_mfma_f32_16x16x32_bf16 v[94:97], v[146:149], v[186:189], v[94:97]
	v_mfma_f32_16x16x32_bf16 v[82:85], v[138:141], v[194:197], v[82:85]
	v_mfma_f32_16x16x32_bf16 v[78:81], v[146:149], v[194:197], v[78:81]
	v_mfma_f32_16x16x32_bf16 v[122:125], v[150:153], v[166:169], v[122:125]
	v_mfma_f32_16x16x32_bf16 v[118:121], v[158:161], v[166:169], v[118:121]
	v_mfma_f32_16x16x32_bf16 v[106:109], v[150:153], v[174:177], v[106:109]
	v_mfma_f32_16x16x32_bf16 v[102:105], v[158:161], v[174:177], v[102:105]
	v_mfma_f32_16x16x32_bf16 v[90:93], v[150:153], v[182:185], v[90:93]
	v_mfma_f32_16x16x32_bf16 v[86:89], v[158:161], v[182:185], v[86:89]
	v_mfma_f32_16x16x32_bf16 v[74:77], v[150:153], v[190:193], v[74:77]
	v_mfma_f32_16x16x32_bf16 v[70:73], v[158:161], v[190:193], v[70:73]
	v_mfma_f32_16x16x32_bf16 v[122:125], v[154:157], v[170:173], v[122:125]
	v_mfma_f32_16x16x32_bf16 v[118:121], v[162:165], v[170:173], v[118:121]
	v_mfma_f32_16x16x32_bf16 v[106:109], v[154:157], v[178:181], v[106:109]
	v_mfma_f32_16x16x32_bf16 v[102:105], v[162:165], v[178:181], v[102:105]
	v_mfma_f32_16x16x32_bf16 v[90:93], v[154:157], v[186:189], v[90:93]
	v_mfma_f32_16x16x32_bf16 v[86:89], v[162:165], v[186:189], v[86:89]
	v_mfma_f32_16x16x32_bf16 v[74:77], v[154:157], v[194:197], v[74:77]
	v_mfma_f32_16x16x32_bf16 v[70:73], v[162:165], v[194:197], v[70:73]
	s_setprio 0
	s_barrier
	s_add_i32 s58, s46, s31
	v_lshl_add_u64 v[218:219], s[26:27], 0, v[200:201]
	s_mov_b32 m0, s58
	ds_read_b128 v[166:169], v226 offset:16384
	ds_read_b128 v[170:173], v226 offset:17408
	ds_read_b128 v[174:177], v226 offset:18432
	ds_read_b128 v[178:181], v226 offset:19456
	ds_read_b128 v[182:185], v226 offset:20480
	ds_read_b128 v[186:189], v226 offset:21504
	ds_read_b128 v[190:193], v226 offset:22528
	ds_read_b128 v[194:197], v226 offset:23552
	global_load_lds_dwordx4 v[218:219], off
	s_add_i32 m0, s58, 0x2000
	s_add_u32 s58, s26, 0x10000
	v_lshl_add_u64 v[220:221], s[26:27], 0, v[204:205]
	s_addc_u32 s59, s27, 0
	s_add_i32 s65, s47, s31
	global_load_lds_dwordx4 v[220:221], off
	v_lshl_add_u64 v[4:5], s[58:59], 0, v[200:201]
	s_mov_b32 m0, s65
	v_lshl_add_u64 v[228:229], s[28:29], 0, v[198:199]
	global_load_lds_dwordx4 v[4:5], off
	v_lshl_add_u64 v[4:5], s[58:59], 0, v[204:205]
	s_add_i32 m0, s65, 0x2000
	v_lshl_add_u64 v[230:231], s[28:29], 0, v[202:203]
	global_load_lds_dwordx4 v[4:5], off
	s_mov_b32 m0, s33
	s_nop 0
	global_load_lds_dwordx4 v[228:229], off
	s_mov_b32 m0, s34
	s_nop 0
	global_load_lds_dwordx4 v[230:231], off
	s_waitcnt vmcnt(8)
	s_waitcnt lgkmcnt(0)
	s_barrier
; #define PG8_STAGE(bufoff, gbase, voff) do { _Pragma("unroll") for (int _i = 0; _i < 2; ++_i) \
;         __builtin_amdgcn_global_load_lds((const unsigned*)((const char*)(gbase) + (voff)[_i]), (PG8_LAS unsigned*)(lds + (bufoff) + ldsw + _i * 8192), 16, 0, 0); } while (0)
; #define PG8_LDA(dst, b, h) do { _Pragma("unroll") for (int m = 0; m < 4; ++m) _Pragma("unroll") for (int k = 0; k < 2; ++k) dst[m][k] = *(const PG8_LAS bf16x8*)(lds + PG8_SA(b, h) + aoff + m * 2048 + k * 1024); } while (0)
; #define PG8_LDB(dst, b, h) do { _Pragma("unroll") for (int n = 0; n < 2; ++n) _Pragma("unroll") for (int k = 0; k < 2; ++k) dst[n][k] = *(const PG8_LAS bf16x8*)(lds + PG8_SB(b, h) + boff + n * 2048 + k * 1024); } while (0)
; #define PG8_MMA(ai, bj, At, Bt) do { __builtin_amdgcn_s_setprio(1); _Pragma("unroll") for (int m = 0; m < 4; ++m) _Pragma("unroll") for (int n = 0; n < 2; ++n) _Pragma("unroll") for (int k = 0; k < 2; ++k) \
;         acc[ai][bj][m][n] = __builtin_amdgcn_mfma_f32_16x16x32_bf16(Bt[n][k], At[m][k], acc[ai][bj][m][n], 0, 0, 0); __builtin_amdgcn_s_setprio(0); } while (0)
; #define PG8_WAIT_V(n) asm volatile("s_waitcnt vmcnt(" #n ")" ::: "memory")
; #define PG8_WAIT_L(n) asm volatile("s_waitcnt lgkmcnt(" #n ")" ::: "memory")
; #define PG8_BAR __builtin_amdgcn_s_barrier()
; #define PG8_SCHED __builtin_amdgcn_sched_barrier(0)
; template <class Epi, class Sched, bool ALIGN_EPI = false, bool SP2 = false>
; __device__ __forceinline__ void gemm_phase(PG8_LAS unsigned char* lds, const Gemm g, const Sched& S, const Epi& E) {
;     ...
;             PG8_WAIT_V(8); PG8_WAIT_L(0); PG8_BAR; PG8_MMA(1, 0, At, B0); PG8_MMA(1, 1, At, B1); PG8_BAR; PG8_SCHED;
;             PG8_LDB(B0, 1, 0); PG8_LDB(B1, 1, 1); PG8_SCHED; PG8_LDA(At, 1, 0); PG8_STAGE(PG8_SA(0, 1), a2 + hstep, voffA);
;             PG8_WAIT_V(8); PG8_WAIT_L(0); PG8_BAR; PG8_MMA(0, 0, At, B0); PG8_MMA(0, 1, At, B1); PG8_BAR; PG8_SCHED;
	s_setprio 1
	s_waitcnt lgkmcnt(0)
	v_mfma_f32_16x16x32_bf16 v[66:69], v[134:137], v[166:169], v[66:69]
	v_mfma_f32_16x16x32_bf16 v[62:65], v[142:145], v[166:169], v[62:65]
	v_mfma_f32_16x16x32_bf16 v[50:53], v[134:137], v[174:177], v[50:53]
	v_mfma_f32_16x16x32_bf16 v[46:49], v[142:145], v[174:177], v[46:49]
	v_mfma_f32_16x16x32_bf16 v[34:37], v[134:137], v[182:185], v[34:37]
	v_mfma_f32_16x16x32_bf16 v[30:33], v[142:145], v[182:185], v[30:33]
	v_mfma_f32_16x16x32_bf16 v[18:21], v[134:137], v[190:193], v[18:21]
	v_mfma_f32_16x16x32_bf16 v[14:17], v[142:145], v[190:193], v[14:17]
	v_mfma_f32_16x16x32_bf16 v[66:69], v[138:141], v[170:173], v[66:69]
	v_mfma_f32_16x16x32_bf16 v[62:65], v[146:149], v[170:173], v[62:65]
	v_mfma_f32_16x16x32_bf16 v[50:53], v[138:141], v[178:181], v[50:53]
	v_mfma_f32_16x16x32_bf16 v[46:49], v[146:149], v[178:181], v[46:49]
	v_mfma_f32_16x16x32_bf16 v[34:37], v[138:141], v[186:189], v[34:37]
	v_mfma_f32_16x16x32_bf16 v[30:33], v[146:149], v[186:189], v[30:33]
	v_mfma_f32_16x16x32_bf16 v[18:21], v[138:141], v[194:197], v[18:21]
	v_mfma_f32_16x16x32_bf16 v[14:17], v[146:149], v[194:197], v[14:17]
	v_mfma_f32_16x16x32_bf16 v[58:61], v[150:153], v[166:169], v[58:61]
	v_mfma_f32_16x16x32_bf16 v[54:57], v[158:161], v[166:169], v[54:57]
	v_mfma_f32_16x16x32_bf16 v[42:45], v[150:153], v[174:177], v[42:45]
	v_mfma_f32_16x16x32_bf16 v[38:41], v[158:161], v[174:177], v[38:41]
	v_mfma_f32_16x16x32_bf16 v[26:29], v[150:153], v[182:185], v[26:29]
	v_mfma_f32_16x16x32_bf16 v[22:25], v[158:161], v[182:185], v[22:25]
	v_mfma_f32_16x16x32_bf16 v[10:13], v[150:153], v[190:193], v[10:13]
	v_mfma_f32_16x16x32_bf16 v[4:7], v[158:161], v[190:193], v[6:9]
	v_mfma_f32_16x16x32_bf16 v[58:61], v[154:157], v[170:173], v[58:61]
	v_mfma_f32_16x16x32_bf16 v[54:57], v[162:165], v[170:173], v[54:57]
	v_mfma_f32_16x16x32_bf16 v[42:45], v[154:157], v[178:181], v[42:45]
	v_mfma_f32_16x16x32_bf16 v[38:41], v[162:165], v[178:181], v[38:41]
	v_mfma_f32_16x16x32_bf16 v[26:29], v[154:157], v[186:189], v[26:29]
	v_mfma_f32_16x16x32_bf16 v[22:25], v[162:165], v[186:189], v[22:25]
	v_mfma_f32_16x16x32_bf16 v[10:13], v[154:157], v[194:197], v[10:13]
	v_mfma_f32_16x16x32_bf16 v[4:7], v[162:165], v[194:197], v[4:7]
	s_setprio 0
	s_barrier
	s_add_i32 s58, 0, 0x18000
	v_add_u32_e32 v3, s58, v224
	s_add_i32 s59, 0, 0x1c000
	ds_read_b128 v[134:137], v3
	ds_read_b128 v[138:141], v3 offset:1024
	ds_read_b128 v[142:145], v3 offset:2048
	ds_read_b128 v[146:149], v3 offset:3072
	v_add_u32_e32 v3, s59, v224
	ds_read_b128 v[150:153], v3
	ds_read_b128 v[154:157], v3 offset:1024
	ds_read_b128 v[158:161], v3 offset:2048
	ds_read_b128 v[162:165], v3 offset:3072
	s_add_u32 s28, s28, 0x40000
	s_addc_u32 s29, s29, 0
	s_mov_b32 m0, s35
	v_lshl_add_u64 v[8:9], s[28:29], 0, v[198:199]
	ds_read_b128 v[166:169], v226 offset:32768
	ds_read_b128 v[170:173], v226 offset:33792
	ds_read_b128 v[174:177], v226 offset:34816
	ds_read_b128 v[178:181], v226 offset:35840
	ds_read_b128 v[182:185], v226 offset:36864
	ds_read_b128 v[186:189], v226 offset:37888
	ds_read_b128 v[190:193], v226 offset:38912
	ds_read_b128 v[194:197], v226 offset:39936
	global_load_lds_dwordx4 v[8:9], off
	v_lshl_add_u64 v[8:9], s[28:29], 0, v[202:203]
	s_mov_b32 m0, s36
	s_nop 0
	global_load_lds_dwordx4 v[8:9], off
	s_waitcnt vmcnt(8)
	s_waitcnt lgkmcnt(0)
	s_barrier
	s_setprio 1
	s_waitcnt lgkmcnt(0)
	v_mfma_f32_16x16x32_bf16 v[130:133], v[134:137], v[166:169], v[130:133]
	v_mfma_f32_16x16x32_bf16 v[126:129], v[142:145], v[166:169], v[126:129]
	v_mfma_f32_16x16x32_bf16 v[114:117], v[134:137], v[174:177], v[114:117]
	v_mfma_f32_16x16x32_bf16 v[110:113], v[142:145], v[174:177], v[110:113]
	v_mfma_f32_16x16x32_bf16 v[98:101], v[134:137], v[182:185], v[98:101]
	v_mfma_f32_16x16x32_bf16 v[94:97], v[142:145], v[182:185], v[94:97]
	v_mfma_f32_16x16x32_bf16 v[82:85], v[134:137], v[190:193], v[82:85]
	v_mfma_f32_16x16x32_bf16 v[78:81], v[142:145], v[190:193], v[78:81]
	v_mfma_f32_16x16x32_bf16 v[130:133], v[138:141], v[170:173], v[130:133]
	v_mfma_f32_16x16x32_bf16 v[126:129], v[146:149], v[170:173], v[126:129]
	v_mfma_f32_16x16x32_bf16 v[114:117], v[138:141], v[178:181], v[114:117]
	v_mfma_f32_16x16x32_bf16 v[110:113], v[146:149], v[178:181], v[110:113]
	v_mfma_f32_16x16x32_bf16 v[98:101], v[138:141], v[186:189], v[98:101]
	v_mfma_f32_16x16x32_bf16 v[94:97], v[146:149], v[186:189], v[94:97]
	v_mfma_f32_16x16x32_bf16 v[82:85], v[138:141], v[194:197], v[82:85]
	v_mfma_f32_16x16x32_bf16 v[78:81], v[146:149], v[194:197], v[78:81]
	v_mfma_f32_16x16x32_bf16 v[122:125], v[150:153], v[166:169], v[122:125]
	v_mfma_f32_16x16x32_bf16 v[118:121], v[158:161], v[166:169], v[118:121]
	v_mfma_f32_16x16x32_bf16 v[106:109], v[150:153], v[174:177], v[106:109]
	v_mfma_f32_16x16x32_bf16 v[102:105], v[158:161], v[174:177], v[102:105]
	v_mfma_f32_16x16x32_bf16 v[90:93], v[150:153], v[182:185], v[90:93]
	v_mfma_f32_16x16x32_bf16 v[86:89], v[158:161], v[182:185], v[86:89]
	v_mfma_f32_16x16x32_bf16 v[74:77], v[150:153], v[190:193], v[74:77]
	v_mfma_f32_16x16x32_bf16 v[70:73], v[158:161], v[190:193], v[70:73]
	v_mfma_f32_16x16x32_bf16 v[122:125], v[154:157], v[170:173], v[122:125]
	v_mfma_f32_16x16x32_bf16 v[118:121], v[162:165], v[170:173], v[118:121]
	v_mfma_f32_16x16x32_bf16 v[106:109], v[154:157], v[178:181], v[106:109]
	v_mfma_f32_16x16x32_bf16 v[102:105], v[162:165], v[178:181], v[102:105]
	v_mfma_f32_16x16x32_bf16 v[90:93], v[154:157], v[186:189], v[90:93]
	v_mfma_f32_16x16x32_bf16 v[86:89], v[162:165], v[186:189], v[86:89]
	v_mfma_f32_16x16x32_bf16 v[74:77], v[154:157], v[194:197], v[74:77]
	v_mfma_f32_16x16x32_bf16 v[70:73], v[162:165], v[194:197], v[70:73]
	s_setprio 0
	s_barrier
; #define PG8_STAGE(bufoff, gbase, voff) do { _Pragma("unroll") for (int _i = 0; _i < 2; ++_i) \
;         __builtin_amdgcn_global_load_lds((const unsigned*)((const char*)(gbase) + (voff)[_i]), (PG8_LAS unsigned*)(lds + (bufoff) + ldsw + _i * 8192), 16, 0, 0); } while (0)
; #define PG8_LDA(dst, b, h) do { _Pragma("unroll") for (int m = 0; m < 4; ++m) _Pragma("unroll") for (int k = 0; k < 2; ++k) dst[m][k] = *(const PG8_LAS bf16x8*)(lds + PG8_SA(b, h) + aoff + m * 2048 + k * 1024); } while (0)
; #define PG8_MMA(ai, bj, At, Bt) do { __builtin_amdgcn_s_setprio(1); _Pragma("unroll") for (int m = 0; m < 4; ++m) _Pragma("unroll") for (int n = 0; n < 2; ++n) _Pragma("unroll") for (int k = 0; k < 2; ++k) \
;         acc[ai][bj][m][n] = __builtin_amdgcn_mfma_f32_16x16x32_bf16(Bt[n][k], At[m][k], acc[ai][bj][m][n], 0, 0, 0); __builtin_amdgcn_s_setprio(0); } while (0)
; #define PG8_WAIT_V(n) asm volatile("s_waitcnt vmcnt(" #n ")" ::: "memory")
; #define PG8_WAIT_L(n) asm volatile("s_waitcnt lgkmcnt(" #n ")" ::: "memory")
; #define PG8_BAR __builtin_amdgcn_s_barrier()
; #define PG8_SCHED __builtin_amdgcn_sched_barrier(0)
; template <class Epi, class Sched, bool ALIGN_EPI = false, bool SP2 = false>
; __device__ __forceinline__ void gemm_phase(PG8_LAS unsigned char* lds, const Gemm g, const Sched& S, const Epi& E) {
;     ...
;             PG8_LDA(At, 1, 1); PG8_STAGE(PG8_SB(1, 0), b3, voffB); PG8_STAGE(PG8_SB(1, 1), b3 + hstepB, voffB); PG8_STAGE(PG8_SA(1, 0), a3, voffA);
;             PG8_WAIT_V(8); PG8_WAIT_L(0); PG8_BAR; PG8_MMA(1, 0, At, B0); PG8_MMA(1, 1, At, B1); PG8_BAR; PG8_SCHED;
	s_add_i32 s28, s58, s31
	v_lshl_add_u64 v[8:9], v[218:219], 0, s[10:11]
	s_mov_b32 m0, s28
	ds_read_b128 v[166:169], v226 offset:49152
	ds_read_b128 v[170:173], v226 offset:50176
	ds_read_b128 v[174:177], v226 offset:51200
	ds_read_b128 v[178:181], v226 offset:52224
	ds_read_b128 v[182:185], v226 offset:53248
	ds_read_b128 v[186:189], v226 offset:54272
	ds_read_b128 v[190:193], v226 offset:55296
	ds_read_b128 v[194:197], v226 offset:56320
	global_load_lds_dwordx4 v[8:9], off
	s_add_i32 m0, s28, 0x2000
	s_add_u32 s26, s26, 0x10080
	v_lshl_add_u64 v[8:9], v[220:221], 0, s[10:11]
	s_addc_u32 s27, s27, 0
	s_add_i32 s28, s59, s31
	global_load_lds_dwordx4 v[8:9], off
	v_lshl_add_u64 v[8:9], s[26:27], 0, v[200:201]
	s_mov_b32 m0, s28
	s_nop 0
	global_load_lds_dwordx4 v[8:9], off
	v_lshl_add_u64 v[8:9], s[26:27], 0, v[204:205]
	s_add_i32 m0, s28, 0x2000
	s_nop 0
	global_load_lds_dwordx4 v[8:9], off
	v_lshl_add_u64 v[8:9], v[228:229], 0, s[10:11]
	s_mov_b32 m0, s39
	s_nop 0
	global_load_lds_dwordx4 v[8:9], off
	v_lshl_add_u64 v[8:9], v[230:231], 0, s[10:11]
	s_mov_b32 m0, s42
	s_nop 0
	global_load_lds_dwordx4 v[8:9], off
	s_waitcnt vmcnt(8)
	s_waitcnt lgkmcnt(0)
	s_barrier
	s_setprio 1
	s_waitcnt lgkmcnt(0)
	v_mfma_f32_16x16x32_bf16 v[66:69], v[134:137], v[166:169], v[66:69]
	v_mfma_f32_16x16x32_bf16 v[62:65], v[142:145], v[166:169], v[62:65]
	v_mfma_f32_16x16x32_bf16 v[50:53], v[134:137], v[174:177], v[50:53]
	v_mfma_f32_16x16x32_bf16 v[46:49], v[142:145], v[174:177], v[46:49]
	v_mfma_f32_16x16x32_bf16 v[34:37], v[134:137], v[182:185], v[34:37]
	v_mfma_f32_16x16x32_bf16 v[30:33], v[142:145], v[182:185], v[30:33]
	v_mfma_f32_16x16x32_bf16 v[18:21], v[134:137], v[190:193], v[18:21]
	v_mfma_f32_16x16x32_bf16 v[14:17], v[142:145], v[190:193], v[14:17]
	v_mfma_f32_16x16x32_bf16 v[66:69], v[138:141], v[170:173], v[66:69]
	v_mfma_f32_16x16x32_bf16 v[62:65], v[146:149], v[170:173], v[62:65]
	v_mfma_f32_16x16x32_bf16 v[50:53], v[138:141], v[178:181], v[50:53]
	v_mfma_f32_16x16x32_bf16 v[46:49], v[146:149], v[178:181], v[46:49]
	v_mfma_f32_16x16x32_bf16 v[34:37], v[138:141], v[186:189], v[34:37]
	v_mfma_f32_16x16x32_bf16 v[30:33], v[146:149], v[186:189], v[30:33]
	v_mfma_f32_16x16x32_bf16 v[18:21], v[138:141], v[194:197], v[18:21]
	v_mfma_f32_16x16x32_bf16 v[14:17], v[146:149], v[194:197], v[14:17]
	v_mfma_f32_16x16x32_bf16 v[58:61], v[150:153], v[166:169], v[58:61]
	v_mfma_f32_16x16x32_bf16 v[54:57], v[158:161], v[166:169], v[54:57]
	v_mfma_f32_16x16x32_bf16 v[42:45], v[150:153], v[174:177], v[42:45]
	v_mfma_f32_16x16x32_bf16 v[38:41], v[158:161], v[174:177], v[38:41]
	v_mfma_f32_16x16x32_bf16 v[26:29], v[150:153], v[182:185], v[26:29]
	v_mfma_f32_16x16x32_bf16 v[22:25], v[158:161], v[182:185], v[22:25]
	v_mfma_f32_16x16x32_bf16 v[8:11], v[150:153], v[190:193], v[10:13]
	v_mfma_f32_16x16x32_bf16 v[4:7], v[158:161], v[190:193], v[4:7]
	v_mfma_f32_16x16x32_bf16 v[58:61], v[154:157], v[170:173], v[58:61]
	v_mfma_f32_16x16x32_bf16 v[54:57], v[162:165], v[170:173], v[54:57]
	v_mfma_f32_16x16x32_bf16 v[42:45], v[154:157], v[178:181], v[42:45]
	v_mfma_f32_16x16x32_bf16 v[38:41], v[162:165], v[178:181], v[38:41]
	v_mfma_f32_16x16x32_bf16 v[26:29], v[154:157], v[186:189], v[26:29]
	v_mfma_f32_16x16x32_bf16 v[22:25], v[162:165], v[186:189], v[22:25]
	v_mfma_f32_16x16x32_bf16 v[10:13], v[154:157], v[194:197], v[8:11]
	v_mfma_f32_16x16x32_bf16 v[6:9], v[162:165], v[194:197], v[4:7]
	s_setprio 0
	s_barrier
	s_add_i32 s64, s64, 2
	s_add_u32 s24, s24, 0x100
	s_addc_u32 s25, s25, 0
	s_cmp_gt_u32 s64, 13
	s_cbranch_scc1 .LBB0_1097

; #define PG8_STAGE(bufoff, gbase, voff) do { _Pragma("unroll") for (int _i = 0; _i < 2; ++_i) \
;         __builtin_amdgcn_global_load_lds((const unsigned*)((const char*)(gbase) + (voff)[_i]), (PG8_LAS unsigned*)(lds + (bufoff) + ldsw + _i * 8192), 16, 0, 0); } while (0)
; #define PG8_LDA(dst, b, h) do { _Pragma("unroll") for (int m = 0; m < 4; ++m) _Pragma("unroll") for (int k = 0; k < 2; ++k) dst[m][k] = *(const PG8_LAS bf16x8*)(lds + PG8_SA(b, h) + aoff + m * 2048 + k * 1024); } while (0)
; #define PG8_LDB(dst, b, h) do { _Pragma("unroll") for (int n = 0; n < 2; ++n) _Pragma("unroll") for (int k = 0; k < 2; ++k) dst[n][k] = *(const PG8_LAS bf16x8*)(lds + PG8_SB(b, h) + boff + n * 2048 + k * 1024); } while (0)
; #define PG8_MMA(ai, bj, At, Bt) do { __builtin_amdgcn_s_setprio(1); _Pragma("unroll") for (int m = 0; m < 4; ++m) _Pragma("unroll") for (int n = 0; n < 2; ++n) _Pragma("unroll") for (int k = 0; k < 2; ++k) \
;         acc[ai][bj][m][n] = __builtin_amdgcn_mfma_f32_16x16x32_bf16(Bt[n][k], At[m][k], acc[ai][bj][m][n], 0, 0, 0); __builtin_amdgcn_s_setprio(0); } while (0)
; #define PG8_WAIT_V(n) asm volatile("s_waitcnt vmcnt(" #n ")" ::: "memory")
; #define PG8_WAIT_L(n) asm volatile("s_waitcnt lgkmcnt(" #n ")" ::: "memory")
; #define PG8_BAR __builtin_amdgcn_s_barrier()
; #define PG8_SCHED __builtin_amdgcn_sched_barrier(0)
; template <class Epi, class Sched, bool ALIGN_EPI = false, bool SP2 = false>
; __device__ __forceinline__ void gemm_phase(PG8_LAS unsigned char* lds, const Gemm g, const Sched& S, const Epi& E) {
;     ...
;             PG8_LDB(B0, 0, 0); PG8_LDB(B1, 0, 1); PG8_SCHED; PG8_LDA(At, 0, 0); PG8_STAGE(PG8_SA(1, 1), a1 + hstep, voffA);
;             PG8_WAIT_V(8); PG8_WAIT_L(0); PG8_BAR; PG8_MMA(0, 0, At, B0); PG8_MMA(0, 1, At, B1); PG8_BAR; PG8_SCHED;
;             PG8_LDA(At, 0, 1); PG8_STAGE(PG8_SB(0, 0), b2, voffB); PG8_STAGE(PG8_SB(0, 1), b2 + hstepB, voffB); PG8_STAGE(PG8_SA(0, 0), a2, voffA);
;             PG8_WAIT_V(8); PG8_WAIT_L(0); PG8_BAR; PG8_MMA(1, 0, At, B0); PG8_MMA(1, 1, At, B1); PG8_BAR; PG8_SCHED;
.LBB0_1180:
	v_add_u32_e32 v144, s55, v142
	ds_read_b128 v[154:157], v144
	ds_read_b128 v[158:161], v144 offset:1024
	ds_read_b128 v[162:165], v144 offset:2048
	ds_read_b128 v[166:169], v144 offset:3072
	v_add_u32_e32 v144, s56, v142
	s_add_u32 s34, s10, s28
	ds_read_b128 v[170:173], v144
	ds_read_b128 v[174:177], v144 offset:1024
	ds_read_b128 v[178:181], v144 offset:2048
	ds_read_b128 v[182:185], v144 offset:3072
	s_addc_u32 s35, s11, s29
	s_add_u32 s34, s34, 0x100
	s_addc_u32 s35, s35, 0
	s_add_u32 s61, s25, s28
	s_addc_u32 s62, s57, s29
	s_cmpk_eq_i32 s28, 0x700
	s_cselect_b32 s37, s21, s35
	s_cselect_b32 s36, s58, s34
	s_cselect_b32 s35, s19, s62
	s_cselect_b32 s34, s59, s61
	v_lshl_add_u64 v[144:145], v[138:139], 0, s[28:29]
	s_add_i32 m0, s39, 0xc000
	ds_read_b128 v[186:189], v143
	ds_read_b128 v[190:193], v143 offset:1024
	ds_read_b128 v[194:197], v143 offset:2048
	ds_read_b128 v[198:201], v143 offset:3072
	ds_read_b128 v[202:205], v143 offset:4096
	ds_read_b128 v[206:209], v143 offset:5120
	ds_read_b128 v[216:219], v143 offset:6144
	ds_read_b128 v[224:227], v143 offset:7168
	global_load_lds_dwordx4 v[144:145], off
	v_lshl_add_u64 v[144:145], v[140:141], 0, s[28:29]
	s_add_i32 m0, s39, 0xe000
	s_nop 0
	global_load_lds_dwordx4 v[144:145], off
	s_waitcnt vmcnt(8)
	s_waitcnt lgkmcnt(0)
	s_barrier
	s_setprio 1
	s_waitcnt lgkmcnt(0)
	v_mfma_f32_16x16x32_bf16 v[150:153], v[154:157], v[186:189], v[150:153]
	v_mfma_f32_16x16x32_bf16 v[144:147], v[162:165], v[186:189], v[146:149]
	v_mfma_f32_16x16x32_bf16 v[110:113], v[154:157], v[194:197], v[110:113]
	v_mfma_f32_16x16x32_bf16 v[106:109], v[162:165], v[194:197], v[106:109]
	v_mfma_f32_16x16x32_bf16 v[94:97], v[154:157], v[202:205], v[94:97]
	v_mfma_f32_16x16x32_bf16 v[90:93], v[162:165], v[202:205], v[90:93]
	v_mfma_f32_16x16x32_bf16 v[78:81], v[154:157], v[216:219], v[78:81]
	v_mfma_f32_16x16x32_bf16 v[74:77], v[162:165], v[216:219], v[74:77]
	v_mfma_f32_16x16x32_bf16 v[150:153], v[158:161], v[190:193], v[150:153]
	v_mfma_f32_16x16x32_bf16 v[144:147], v[166:169], v[190:193], v[144:147]
	v_mfma_f32_16x16x32_bf16 v[110:113], v[158:161], v[198:201], v[110:113]
	v_mfma_f32_16x16x32_bf16 v[106:109], v[166:169], v[198:201], v[106:109]
	v_mfma_f32_16x16x32_bf16 v[94:97], v[158:161], v[206:209], v[94:97]
	v_mfma_f32_16x16x32_bf16 v[90:93], v[166:169], v[206:209], v[90:93]
	v_mfma_f32_16x16x32_bf16 v[78:81], v[158:161], v[224:227], v[78:81]
	v_mfma_f32_16x16x32_bf16 v[74:77], v[166:169], v[224:227], v[74:77]
	v_mfma_f32_16x16x32_bf16 v[118:121], v[170:173], v[186:189], v[118:121]
	v_mfma_f32_16x16x32_bf16 v[114:117], v[178:181], v[186:189], v[114:117]
	v_mfma_f32_16x16x32_bf16 v[102:105], v[170:173], v[194:197], v[102:105]
	v_mfma_f32_16x16x32_bf16 v[98:101], v[178:181], v[194:197], v[98:101]
	v_mfma_f32_16x16x32_bf16 v[86:89], v[170:173], v[202:205], v[86:89]
	v_mfma_f32_16x16x32_bf16 v[82:85], v[178:181], v[202:205], v[82:85]
	v_mfma_f32_16x16x32_bf16 v[70:73], v[170:173], v[216:219], v[70:73]
	v_mfma_f32_16x16x32_bf16 v[66:69], v[178:181], v[216:219], v[66:69]
	v_mfma_f32_16x16x32_bf16 v[118:121], v[174:177], v[190:193], v[118:121]
	v_mfma_f32_16x16x32_bf16 v[114:117], v[182:185], v[190:193], v[114:117]
	v_mfma_f32_16x16x32_bf16 v[102:105], v[174:177], v[198:201], v[102:105]
	v_mfma_f32_16x16x32_bf16 v[98:101], v[182:185], v[198:201], v[98:101]
	v_mfma_f32_16x16x32_bf16 v[86:89], v[174:177], v[206:209], v[86:89]
	v_mfma_f32_16x16x32_bf16 v[82:85], v[182:185], v[206:209], v[82:85]
	v_mfma_f32_16x16x32_bf16 v[70:73], v[174:177], v[224:227], v[70:73]
	v_mfma_f32_16x16x32_bf16 v[66:69], v[182:185], v[224:227], v[66:69]
	s_setprio 0
	s_barrier
	s_add_i32 s61, s55, s38
	v_lshl_add_u64 v[210:211], s[34:35], 0, v[124:125]
	s_mov_b32 m0, s61
	ds_read_b128 v[186:189], v143 offset:16384
	ds_read_b128 v[190:193], v143 offset:17408
	ds_read_b128 v[194:197], v143 offset:18432
	ds_read_b128 v[198:201], v143 offset:19456
	ds_read_b128 v[202:205], v143 offset:20480
	ds_read_b128 v[206:209], v143 offset:21504
	ds_read_b128 v[216:219], v143 offset:22528
	ds_read_b128 v[224:227], v143 offset:23552
	global_load_lds_dwordx4 v[210:211], off
	s_add_i32 m0, s61, 0x2000
	s_add_u32 s62, s34, 0x10000
	v_lshl_add_u64 v[220:221], s[34:35], 0, v[128:129]
	s_addc_u32 s63, s35, 0
	s_add_i32 s61, s56, s38
	global_load_lds_dwordx4 v[220:221], off
	v_lshl_add_u64 v[148:149], s[62:63], 0, v[124:125]
	s_mov_b32 m0, s61
	v_lshl_add_u64 v[228:229], s[36:37], 0, v[122:123]
	global_load_lds_dwordx4 v[148:149], off
	v_lshl_add_u64 v[148:149], s[62:63], 0, v[128:129]
	s_add_i32 m0, s61, 0x2000
	v_lshl_add_u64 v[230:231], s[36:37], 0, v[126:127]
	global_load_lds_dwordx4 v[148:149], off
	s_mov_b32 m0, s39
	s_nop 0
	global_load_lds_dwordx4 v[228:229], off
	s_mov_b32 m0, s42
	s_nop 0
	global_load_lds_dwordx4 v[230:231], off
	s_waitcnt vmcnt(8)
	s_waitcnt lgkmcnt(0)
	s_barrier
; #define PG8_STAGE(bufoff, gbase, voff) do { _Pragma("unroll") for (int _i = 0; _i < 2; ++_i) \
;         __builtin_amdgcn_global_load_lds((const unsigned*)((const char*)(gbase) + (voff)[_i]), (PG8_LAS unsigned*)(lds + (bufoff) + ldsw + _i * 8192), 16, 0, 0); } while (0)
; #define PG8_LDA(dst, b, h) do { _Pragma("unroll") for (int m = 0; m < 4; ++m) _Pragma("unroll") for (int k = 0; k < 2; ++k) dst[m][k] = *(const PG8_LAS bf16x8*)(lds + PG8_SA(b, h) + aoff + m * 2048 + k * 1024); } while (0)
; #define PG8_LDB(dst, b, h) do { _Pragma("unroll") for (int n = 0; n < 2; ++n) _Pragma("unroll") for (int k = 0; k < 2; ++k) dst[n][k] = *(const PG8_LAS bf16x8*)(lds + PG8_SB(b, h) + boff + n * 2048 + k * 1024); } while (0)
; #define PG8_MMA(ai, bj, At, Bt) do { __builtin_amdgcn_s_setprio(1); _Pragma("unroll") for (int m = 0; m < 4; ++m) _Pragma("unroll") for (int n = 0; n < 2; ++n) _Pragma("unroll") for (int k = 0; k < 2; ++k) \
;         acc[ai][bj][m][n] = __builtin_amdgcn_mfma_f32_16x16x32_bf16(Bt[n][k], At[m][k], acc[ai][bj][m][n], 0, 0, 0); __builtin_amdgcn_s_setprio(0); } while (0)
; #define PG8_WAIT_V(n) asm volatile("s_waitcnt vmcnt(" #n ")" ::: "memory")
; #define PG8_WAIT_L(n) asm volatile("s_waitcnt lgkmcnt(" #n ")" ::: "memory")
; #define PG8_BAR __builtin_amdgcn_s_barrier()
; #define PG8_SCHED __builtin_amdgcn_sched_barrier(0)
; template <class Epi, class Sched, bool ALIGN_EPI = false, bool SP2 = false>
; __device__ __forceinline__ void gemm_phase(PG8_LAS unsigned char* lds, const Gemm g, const Sched& S, const Epi& E) {
;     ...
;             PG8_WAIT_V(8); PG8_WAIT_L(0); PG8_BAR; PG8_MMA(1, 0, At, B0); PG8_MMA(1, 1, At, B1); PG8_BAR; PG8_SCHED;
;             PG8_LDB(B0, 1, 0); PG8_LDB(B1, 1, 1); PG8_SCHED; PG8_LDA(At, 1, 0); PG8_STAGE(PG8_SA(0, 1), a2 + hstep, voffA);
;             PG8_WAIT_V(8); PG8_WAIT_L(0); PG8_BAR; PG8_MMA(0, 0, At, B0); PG8_MMA(0, 1, At, B1); PG8_BAR; PG8_SCHED;
	s_setprio 1
	s_waitcnt lgkmcnt(0)
	v_mfma_f32_16x16x32_bf16 v[62:65], v[154:157], v[186:189], v[62:65]
	v_mfma_f32_16x16x32_bf16 v[58:61], v[162:165], v[186:189], v[58:61]
	v_mfma_f32_16x16x32_bf16 v[46:49], v[154:157], v[194:197], v[46:49]
	v_mfma_f32_16x16x32_bf16 v[42:45], v[162:165], v[194:197], v[42:45]
	v_mfma_f32_16x16x32_bf16 v[30:33], v[154:157], v[202:205], v[30:33]
	v_mfma_f32_16x16x32_bf16 v[26:29], v[162:165], v[202:205], v[26:29]
	v_mfma_f32_16x16x32_bf16 v[14:17], v[154:157], v[216:219], v[14:17]
	v_mfma_f32_16x16x32_bf16 v[10:13], v[162:165], v[216:219], v[10:13]
	v_mfma_f32_16x16x32_bf16 v[62:65], v[158:161], v[190:193], v[62:65]
	v_mfma_f32_16x16x32_bf16 v[58:61], v[166:169], v[190:193], v[58:61]
	v_mfma_f32_16x16x32_bf16 v[46:49], v[158:161], v[198:201], v[46:49]
	v_mfma_f32_16x16x32_bf16 v[42:45], v[166:169], v[198:201], v[42:45]
	v_mfma_f32_16x16x32_bf16 v[30:33], v[158:161], v[206:209], v[30:33]
	v_mfma_f32_16x16x32_bf16 v[26:29], v[166:169], v[206:209], v[26:29]
	v_mfma_f32_16x16x32_bf16 v[14:17], v[158:161], v[224:227], v[14:17]
	v_mfma_f32_16x16x32_bf16 v[10:13], v[166:169], v[224:227], v[10:13]
	v_mfma_f32_16x16x32_bf16 v[54:57], v[170:173], v[186:189], v[54:57]
	v_mfma_f32_16x16x32_bf16 v[50:53], v[178:181], v[186:189], v[50:53]
	v_mfma_f32_16x16x32_bf16 v[38:41], v[170:173], v[194:197], v[38:41]
	v_mfma_f32_16x16x32_bf16 v[34:37], v[178:181], v[194:197], v[34:37]
	v_mfma_f32_16x16x32_bf16 v[22:25], v[170:173], v[202:205], v[22:25]
	v_mfma_f32_16x16x32_bf16 v[18:21], v[178:181], v[202:205], v[18:21]
	v_mfma_f32_16x16x32_bf16 v[6:9], v[170:173], v[216:219], v[6:9]
	v_mfma_f32_16x16x32_bf16 v[2:5], v[178:181], v[216:219], v[2:5]
	v_mfma_f32_16x16x32_bf16 v[54:57], v[174:177], v[190:193], v[54:57]
	v_mfma_f32_16x16x32_bf16 v[50:53], v[182:185], v[190:193], v[50:53]
	v_mfma_f32_16x16x32_bf16 v[38:41], v[174:177], v[198:201], v[38:41]
	v_mfma_f32_16x16x32_bf16 v[34:37], v[182:185], v[198:201], v[34:37]
	v_mfma_f32_16x16x32_bf16 v[22:25], v[174:177], v[206:209], v[22:25]
	v_mfma_f32_16x16x32_bf16 v[18:21], v[182:185], v[206:209], v[18:21]
	v_mfma_f32_16x16x32_bf16 v[6:9], v[174:177], v[224:227], v[6:9]
	v_mfma_f32_16x16x32_bf16 v[2:5], v[182:185], v[224:227], v[2:5]
	s_setprio 0
	s_barrier
	s_add_i32 s61, 0, 0x18000
	v_add_u32_e32 v148, s61, v142
	s_add_i32 s62, 0, 0x1c000
	ds_read_b128 v[154:157], v148
	ds_read_b128 v[158:161], v148 offset:1024
	ds_read_b128 v[162:165], v148 offset:2048
	ds_read_b128 v[166:169], v148 offset:3072
	v_add_u32_e32 v148, s62, v142
	ds_read_b128 v[170:173], v148
	ds_read_b128 v[174:177], v148 offset:1024
	ds_read_b128 v[178:181], v148 offset:2048
	ds_read_b128 v[182:185], v148 offset:3072
	s_add_u32 s36, s36, 0x40000
	s_addc_u32 s37, s37, 0
	s_mov_b32 m0, s44
	v_lshl_add_u64 v[148:149], s[36:37], 0, v[122:123]
	ds_read_b128 v[186:189], v143 offset:32768
	ds_read_b128 v[190:193], v143 offset:33792
	ds_read_b128 v[194:197], v143 offset:34816
	ds_read_b128 v[198:201], v143 offset:35840
	ds_read_b128 v[202:205], v143 offset:36864
	ds_read_b128 v[206:209], v143 offset:37888
	ds_read_b128 v[216:219], v143 offset:38912
	ds_read_b128 v[224:227], v143 offset:39936
	global_load_lds_dwordx4 v[148:149], off
	v_lshl_add_u64 v[148:149], s[36:37], 0, v[126:127]
	s_mov_b32 m0, s45
	s_nop 0
	global_load_lds_dwordx4 v[148:149], off
	s_waitcnt vmcnt(8)
	s_waitcnt lgkmcnt(0)
	s_barrier
	s_setprio 1
	s_waitcnt lgkmcnt(0)
	v_mfma_f32_16x16x32_bf16 v[148:151], v[154:157], v[186:189], v[150:153]
	v_mfma_f32_16x16x32_bf16 v[144:147], v[162:165], v[186:189], v[144:147]
	v_mfma_f32_16x16x32_bf16 v[110:113], v[154:157], v[194:197], v[110:113]
	v_mfma_f32_16x16x32_bf16 v[106:109], v[162:165], v[194:197], v[106:109]
	v_mfma_f32_16x16x32_bf16 v[94:97], v[154:157], v[202:205], v[94:97]
	v_mfma_f32_16x16x32_bf16 v[90:93], v[162:165], v[202:205], v[90:93]
	v_mfma_f32_16x16x32_bf16 v[78:81], v[154:157], v[216:219], v[78:81]
	v_mfma_f32_16x16x32_bf16 v[74:77], v[162:165], v[216:219], v[74:77]
	v_mfma_f32_16x16x32_bf16 v[150:153], v[158:161], v[190:193], v[148:151]
	v_mfma_f32_16x16x32_bf16 v[146:149], v[166:169], v[190:193], v[144:147]
	v_mfma_f32_16x16x32_bf16 v[110:113], v[158:161], v[198:201], v[110:113]
	v_mfma_f32_16x16x32_bf16 v[106:109], v[166:169], v[198:201], v[106:109]
	v_mfma_f32_16x16x32_bf16 v[94:97], v[158:161], v[206:209], v[94:97]
	v_mfma_f32_16x16x32_bf16 v[90:93], v[166:169], v[206:209], v[90:93]
	v_mfma_f32_16x16x32_bf16 v[78:81], v[158:161], v[224:227], v[78:81]
	v_mfma_f32_16x16x32_bf16 v[74:77], v[166:169], v[224:227], v[74:77]
	v_mfma_f32_16x16x32_bf16 v[118:121], v[170:173], v[186:189], v[118:121]
	v_mfma_f32_16x16x32_bf16 v[114:117], v[178:181], v[186:189], v[114:117]
	v_mfma_f32_16x16x32_bf16 v[102:105], v[170:173], v[194:197], v[102:105]
	v_mfma_f32_16x16x32_bf16 v[98:101], v[178:181], v[194:197], v[98:101]
	v_mfma_f32_16x16x32_bf16 v[86:89], v[170:173], v[202:205], v[86:89]
	v_mfma_f32_16x16x32_bf16 v[82:85], v[178:181], v[202:205], v[82:85]
	v_mfma_f32_16x16x32_bf16 v[70:73], v[170:173], v[216:219], v[70:73]
	v_mfma_f32_16x16x32_bf16 v[66:69], v[178:181], v[216:219], v[66:69]
	v_mfma_f32_16x16x32_bf16 v[118:121], v[174:177], v[190:193], v[118:121]
	v_mfma_f32_16x16x32_bf16 v[114:117], v[182:185], v[190:193], v[114:117]
	v_mfma_f32_16x16x32_bf16 v[102:105], v[174:177], v[198:201], v[102:105]
	v_mfma_f32_16x16x32_bf16 v[98:101], v[182:185], v[198:201], v[98:101]
	v_mfma_f32_16x16x32_bf16 v[86:89], v[174:177], v[206:209], v[86:89]
	v_mfma_f32_16x16x32_bf16 v[82:85], v[182:185], v[206:209], v[82:85]
	v_mfma_f32_16x16x32_bf16 v[70:73], v[174:177], v[224:227], v[70:73]
	v_mfma_f32_16x16x32_bf16 v[66:69], v[182:185], v[224:227], v[66:69]
	s_setprio 0
	s_barrier
; #define PG8_STAGE(bufoff, gbase, voff) do { _Pragma("unroll") for (int _i = 0; _i < 2; ++_i) \
;         __builtin_amdgcn_global_load_lds((const unsigned*)((const char*)(gbase) + (voff)[_i]), (PG8_LAS unsigned*)(lds + (bufoff) + ldsw + _i * 8192), 16, 0, 0); } while (0)
; #define PG8_LDA(dst, b, h) do { _Pragma("unroll") for (int m = 0; m < 4; ++m) _Pragma("unroll") for (int k = 0; k < 2; ++k) dst[m][k] = *(const PG8_LAS bf16x8*)(lds + PG8_SA(b, h) + aoff + m * 2048 + k * 1024); } while (0)
; #define PG8_MMA(ai, bj, At, Bt) do { __builtin_amdgcn_s_setprio(1); _Pragma("unroll") for (int m = 0; m < 4; ++m) _Pragma("unroll") for (int n = 0; n < 2; ++n) _Pragma("unroll") for (int k = 0; k < 2; ++k) \
;         acc[ai][bj][m][n] = __builtin_amdgcn_mfma_f32_16x16x32_bf16(Bt[n][k], At[m][k], acc[ai][bj][m][n], 0, 0, 0); __builtin_amdgcn_s_setprio(0); } while (0)
; #define PG8_WAIT_V(n) asm volatile("s_waitcnt vmcnt(" #n ")" ::: "memory")
; #define PG8_WAIT_L(n) asm volatile("s_waitcnt lgkmcnt(" #n ")" ::: "memory")
; #define PG8_BAR __builtin_amdgcn_s_barrier()
; #define PG8_SCHED __builtin_amdgcn_sched_barrier(0)
; template <class Epi, class Sched, bool ALIGN_EPI = false, bool SP2 = false>
; __device__ __forceinline__ void gemm_phase(PG8_LAS unsigned char* lds, const Gemm g, const Sched& S, const Epi& E) {
;     ...
;             PG8_LDA(At, 1, 1); PG8_STAGE(PG8_SB(1, 0), b3, voffB); PG8_STAGE(PG8_SB(1, 1), b3 + hstepB, voffB); PG8_STAGE(PG8_SA(1, 0), a3, voffA);
;             PG8_WAIT_V(8); PG8_WAIT_L(0); PG8_BAR; PG8_MMA(1, 0, At, B0); PG8_MMA(1, 1, At, B1); PG8_BAR; PG8_SCHED;
;     ...
; #pragma unroll
;         for (int a = 0; a < 2; ++a)
; #pragma unroll
;             for (int b = 0; b < 2; ++b)
; #pragma unroll
;                 for (int m = 0; m < 4; ++m)
; #pragma unroll
;                     for (int n = 0; n < 2; ++n) acc[a][b][m][n] = (f32x4){0.f, 0.f, 0.f, 0.f};
;         cur = nxt; cA = nA; cB = nB; ++ui;
	s_add_i32 s36, s61, s38
	v_lshl_add_u64 v[144:145], v[210:211], 0, s[16:17]
	s_mov_b32 m0, s36
	ds_read_b128 v[186:189], v143 offset:49152
	ds_read_b128 v[190:193], v143 offset:50176
	ds_read_b128 v[194:197], v143 offset:51200
	ds_read_b128 v[198:201], v143 offset:52224
	ds_read_b128 v[202:205], v143 offset:53248
	ds_read_b128 v[206:209], v143 offset:54272
	ds_read_b128 v[216:219], v143 offset:55296
	ds_read_b128 v[224:227], v143 offset:56320
	global_load_lds_dwordx4 v[144:145], off
	s_add_i32 m0, s36, 0x2000
	s_add_u32 s34, s34, 0x10080
	v_lshl_add_u64 v[144:145], v[220:221], 0, s[16:17]
	s_addc_u32 s35, s35, 0
	s_add_i32 s36, s62, s38
	global_load_lds_dwordx4 v[144:145], off
	v_lshl_add_u64 v[144:145], s[34:35], 0, v[124:125]
	s_mov_b32 m0, s36
	s_nop 0
	global_load_lds_dwordx4 v[144:145], off
	v_lshl_add_u64 v[144:145], s[34:35], 0, v[128:129]
	s_add_i32 m0, s36, 0x2000
	s_nop 0
	global_load_lds_dwordx4 v[144:145], off
	v_lshl_add_u64 v[144:145], v[228:229], 0, s[16:17]
	s_mov_b32 m0, s46
	s_nop 0
	global_load_lds_dwordx4 v[144:145], off
	v_lshl_add_u64 v[144:145], v[230:231], 0, s[16:17]
	s_mov_b32 m0, s47
	s_nop 0
	global_load_lds_dwordx4 v[144:145], off
	s_waitcnt vmcnt(8)
	s_waitcnt lgkmcnt(0)
	s_barrier
	s_setprio 1
	s_waitcnt lgkmcnt(0)
	v_mfma_f32_16x16x32_bf16 v[62:65], v[154:157], v[186:189], v[62:65]
	v_mfma_f32_16x16x32_bf16 v[58:61], v[162:165], v[186:189], v[58:61]
	v_mfma_f32_16x16x32_bf16 v[46:49], v[154:157], v[194:197], v[46:49]
	v_mfma_f32_16x16x32_bf16 v[42:45], v[162:165], v[194:197], v[42:45]
	v_mfma_f32_16x16x32_bf16 v[30:33], v[154:157], v[202:205], v[30:33]
	v_mfma_f32_16x16x32_bf16 v[26:29], v[162:165], v[202:205], v[26:29]
	v_mfma_f32_16x16x32_bf16 v[14:17], v[154:157], v[216:219], v[14:17]
	v_mfma_f32_16x16x32_bf16 v[10:13], v[162:165], v[216:219], v[10:13]
	v_mfma_f32_16x16x32_bf16 v[62:65], v[158:161], v[190:193], v[62:65]
	v_mfma_f32_16x16x32_bf16 v[58:61], v[166:169], v[190:193], v[58:61]
	v_mfma_f32_16x16x32_bf16 v[46:49], v[158:161], v[198:201], v[46:49]
	v_mfma_f32_16x16x32_bf16 v[42:45], v[166:169], v[198:201], v[42:45]
	v_mfma_f32_16x16x32_bf16 v[30:33], v[158:161], v[206:209], v[30:33]
	v_mfma_f32_16x16x32_bf16 v[26:29], v[166:169], v[206:209], v[26:29]
	v_mfma_f32_16x16x32_bf16 v[14:17], v[158:161], v[224:227], v[14:17]
	v_mfma_f32_16x16x32_bf16 v[10:13], v[166:169], v[224:227], v[10:13]
	v_mfma_f32_16x16x32_bf16 v[54:57], v[170:173], v[186:189], v[54:57]
	v_mfma_f32_16x16x32_bf16 v[50:53], v[178:181], v[186:189], v[50:53]
	v_mfma_f32_16x16x32_bf16 v[38:41], v[170:173], v[194:197], v[38:41]
	v_mfma_f32_16x16x32_bf16 v[34:37], v[178:181], v[194:197], v[34:37]
	v_mfma_f32_16x16x32_bf16 v[22:25], v[170:173], v[202:205], v[22:25]
	v_mfma_f32_16x16x32_bf16 v[18:21], v[178:181], v[202:205], v[18:21]
	v_mfma_f32_16x16x32_bf16 v[6:9], v[170:173], v[216:219], v[6:9]
	v_mfma_f32_16x16x32_bf16 v[2:5], v[178:181], v[216:219], v[2:5]
	v_mfma_f32_16x16x32_bf16 v[54:57], v[174:177], v[190:193], v[54:57]
	v_mfma_f32_16x16x32_bf16 v[50:53], v[182:185], v[190:193], v[50:53]
	v_mfma_f32_16x16x32_bf16 v[38:41], v[174:177], v[198:201], v[38:41]
	v_mfma_f32_16x16x32_bf16 v[34:37], v[182:185], v[198:201], v[34:37]
	v_mfma_f32_16x16x32_bf16 v[22:25], v[174:177], v[206:209], v[22:25]
	v_mfma_f32_16x16x32_bf16 v[18:21], v[182:185], v[206:209], v[18:21]
	v_mfma_f32_16x16x32_bf16 v[6:9], v[174:177], v[224:227], v[6:9]
	v_mfma_f32_16x16x32_bf16 v[2:5], v[182:185], v[224:227], v[2:5]
	s_setprio 0
	s_barrier
	s_add_i32 s60, s60, 2
	s_add_u32 s28, s28, 0x100
	s_addc_u32 s29, s29, 0
	s_cmp_gt_u32 s60, 13
	s_cbranch_scc0 .LBB0_1180
	s_add_u32 s28, s25, 0xffffff00
	s_addc_u32 s29, s57, -1
	s_andn2_b64 vcc, exec, s[8:9]
	s_cbranch_vccnz .LBB0_1171
	v_mov_b32_e32 v2, 0
	s_mov_b32 s0, s18
	s_mov_b32 s14, s20
	s_mov_b64 s[10:11], s[26:27]
	s_mov_b32 s54, s24
	v_mov_b32_e32 v3, v2
	v_mov_b32_e32 v4, v2
	v_mov_b32_e32 v5, v2
	v_mov_b32_e32 v6, v2
	v_mov_b32_e32 v7, v2
	v_mov_b32_e32 v8, v2
	v_mov_b32_e32 v9, v2
	v_mov_b32_e32 v18, v2
	v_mov_b32_e32 v19, v2
	v_mov_b32_e32 v20, v2
	v_mov_b32_e32 v21, v2
	v_mov_b32_e32 v22, v2
	v_mov_b32_e32 v23, v2
	v_mov_b32_e32 v24, v2
	v_mov_b32_e32 v25, v2
	v_mov_b32_e32 v34, v2
	v_mov_b32_e32 v35, v2
	v_mov_b32_e32 v36, v2
	v_mov_b32_e32 v37, v2
	v_mov_b32_e32 v38, v2
	v_mov_b32_e32 v39, v2
	v_mov_b32_e32 v40, v2
	v_mov_b32_e32 v41, v2
	v_mov_b32_e32 v50, v2
	v_mov_b32_e32 v51, v2
	v_mov_b32_e32 v52, v2
	v_mov_b32_e32 v53, v2
	v_mov_b32_e32 v54, v2
	v_mov_b32_e32 v55, v2
	v_mov_b32_e32 v56, v2
	v_mov_b32_e32 v57, v2
	v_mov_b32_e32 v10, v2
	v_mov_b32_e32 v11, v2
	v_mov_b32_e32 v12, v2
	v_mov_b32_e32 v13, v2
	v_mov_b32_e32 v14, v2
	v_mov_b32_e32 v15, v2
	v_mov_b32_e32 v16, v2
	v_mov_b32_e32 v17, v2
	v_mov_b32_e32 v26, v2
	v_mov_b32_e32 v27, v2
	v_mov_b32_e32 v28, v2
	v_mov_b32_e32 v29, v2
	v_mov_b32_e32 v30, v2
	v_mov_b32_e32 v31, v2
	v_mov_b32_e32 v32, v2
	v_mov_b32_e32 v33, v2
	v_mov_b32_e32 v42, v2
	v_mov_b32_e32 v43, v2
	v_mov_b32_e32 v44, v2
	v_mov_b32_e32 v45, v2
	v_mov_b32_e32 v46, v2
	v_mov_b32_e32 v47, v2
	v_mov_b32_e32 v48, v2
	v_mov_b32_e32 v49, v2
	v_mov_b32_e32 v58, v2
	v_mov_b32_e32 v59, v2
	v_mov_b32_e32 v60, v2
	v_mov_b32_e32 v61, v2
	v_mov_b32_e32 v62, v2
	v_mov_b32_e32 v63, v2
	v_mov_b32_e32 v64, v2
	v_mov_b32_e32 v65, v2
	v_mov_b32_e32 v66, v2
	v_mov_b32_e32 v67, v2
	v_mov_b32_e32 v68, v2
	v_mov_b32_e32 v69, v2
	v_mov_b32_e32 v70, v2
	v_mov_b32_e32 v71, v2
	v_mov_b32_e32 v72, v2
	v_mov_b32_e32 v73, v2
	v_mov_b32_e32 v82, v2
	v_mov_b32_e32 v83, v2
	v_mov_b32_e32 v84, v2
	v_mov_b32_e32 v85, v2
	v_mov_b32_e32 v86, v2
	v_mov_b32_e32 v87, v2
	v_mov_b32_e32 v88, v2
	v_mov_b32_e32 v89, v2
	v_mov_b32_e32 v98, v2
	v_mov_b32_e32 v99, v2
	v_mov_b32_e32 v100, v2
	v_mov_b32_e32 v101, v2
	v_mov_b32_e32 v102, v2
	v_mov_b32_e32 v103, v2
	v_mov_b32_e32 v104, v2
	v_mov_b32_e32 v105, v2
	v_mov_b32_e32 v114, v2
	v_mov_b32_e32 v115, v2
	v_mov_b32_e32 v116, v2
	v_mov_b32_e32 v117, v2
	v_mov_b32_e32 v118, v2
	v_mov_b32_e32 v119, v2
	v_mov_b32_e32 v120, v2
	v_mov_b32_e32 v121, v2
	v_mov_b32_e32 v74, v2
	v_mov_b32_e32 v75, v2
	v_mov_b32_e32 v76, v2
	v_mov_b32_e32 v77, v2
	v_mov_b32_e32 v78, v2
	v_mov_b32_e32 v79, v2
	v_mov_b32_e32 v80, v2
	v_mov_b32_e32 v81, v2
	v_mov_b32_e32 v90, v2
	v_mov_b32_e32 v91, v2
	v_mov_b32_e32 v92, v2
	v_mov_b32_e32 v93, v2
	v_mov_b32_e32 v94, v2
	v_mov_b32_e32 v95, v2
	v_mov_b32_e32 v96, v2
	v_mov_b32_e32 v97, v2
	v_mov_b32_e32 v106, v2
	v_mov_b32_e32 v107, v2
	v_mov_b32_e32 v108, v2
	v_mov_b32_e32 v109, v2
	v_mov_b32_e32 v110, v2
	v_mov_b32_e32 v111, v2
	v_mov_b32_e32 v112, v2
	v_mov_b32_e32 v113, v2
	v_mov_b32_e32 v146, v2
	v_mov_b32_e32 v147, v2
	v_mov_b32_e32 v148, v2
	v_mov_b32_e32 v149, v2
	v_mov_b32_e32 v150, v2
	v_mov_b32_e32 v151, v2
	v_mov_b32_e32 v152, v2
	v_mov_b32_e32 v153, v2
	s_andn2_b64 vcc, exec, s[6:7]
	s_cbranch_vccnz .LBB0_1172

; #define PG8_STAGE(bufoff, gbase, voff) do { _Pragma("unroll") for (int _i = 0; _i < 2; ++_i) \
;         __builtin_amdgcn_global_load_lds((const unsigned*)((const char*)(gbase) + (voff)[_i]), (PG8_LAS unsigned*)(lds + (bufoff) + ldsw + _i * 8192), 16, 0, 0); } while (0)
; #define PG8_LDA(dst, b, h) do { _Pragma("unroll") for (int m = 0; m < 4; ++m) _Pragma("unroll") for (int k = 0; k < 2; ++k) dst[m][k] = *(const PG8_LAS bf16x8*)(lds + PG8_SA(b, h) + aoff + m * 2048 + k * 1024); } while (0)
; #define PG8_LDB(dst, b, h) do { _Pragma("unroll") for (int n = 0; n < 2; ++n) _Pragma("unroll") for (int k = 0; k < 2; ++k) dst[n][k] = *(const PG8_LAS bf16x8*)(lds + PG8_SB(b, h) + boff + n * 2048 + k * 1024); } while (0)
; #define PG8_MMA(ai, bj, At, Bt) do { __builtin_amdgcn_s_setprio(1); _Pragma("unroll") for (int m = 0; m < 4; ++m) _Pragma("unroll") for (int n = 0; n < 2; ++n) _Pragma("unroll") for (int k = 0; k < 2; ++k) \
;         acc[ai][bj][m][n] = __builtin_amdgcn_mfma_f32_16x16x32_bf16(Bt[n][k], At[m][k], acc[ai][bj][m][n], 0, 0, 0); __builtin_amdgcn_s_setprio(0); } while (0)
; #define PG8_WAIT_V(n) asm volatile("s_waitcnt vmcnt(" #n ")" ::: "memory")
; #define PG8_WAIT_L(n) asm volatile("s_waitcnt lgkmcnt(" #n ")" ::: "memory")
; #define PG8_BAR __builtin_amdgcn_s_barrier()
; #define PG8_SCHED __builtin_amdgcn_sched_barrier(0)
; template <class Epi, class Sched, bool ALIGN_EPI = false, bool SP2 = false>
; __device__ __forceinline__ void gemm_phase(PG8_LAS unsigned char* lds, const Gemm g, const Sched& S, const Epi& E) {
;     ...
;             PG8_LDB(B0, 0, 0); PG8_LDB(B1, 0, 1); PG8_SCHED; PG8_LDA(At, 0, 0); PG8_STAGE(PG8_SA(1, 1), a1 + hstep, voffA);
;             PG8_WAIT_V(8); PG8_WAIT_L(0); PG8_BAR; PG8_MMA(0, 0, At, B0); PG8_MMA(0, 1, At, B1); PG8_BAR; PG8_SCHED;
;             PG8_LDA(At, 0, 1); PG8_STAGE(PG8_SB(0, 0), b2, voffB); PG8_STAGE(PG8_SB(0, 1), b2 + hstepB, voffB); PG8_STAGE(PG8_SA(0, 0), a2, voffA);
.LBB0_1313:
	ds_read_b128 v[146:149], v154
	ds_read_b128 v[158:161], v154 offset:1024
	ds_read_b128 v[162:165], v154 offset:2048
	ds_read_b128 v[166:169], v154 offset:3072
	ds_read_b128 v[170:173], v155
	ds_read_b128 v[174:177], v155 offset:1024
	ds_read_b128 v[178:181], v155 offset:2048
	ds_read_b128 v[182:185], v155 offset:3072
	s_add_u32 s40, s38, 0xfffc0080
	s_addc_u32 s41, s39, -1
	s_cmp_eq_u32 s61, 12
	s_cselect_b32 s43, s9, s41
	s_cselect_b32 s42, s27, s40
	s_cselect_b32 s41, s25, s60
	s_cselect_b32 s40, s37, s59
	v_lshl_add_u64 v[150:151], s[38:39], 0, v[138:139]
	s_add_i32 m0, s31, 0xc000
	ds_read_b128 v[186:189], v156
	ds_read_b128 v[190:193], v156 offset:1024
	ds_read_b128 v[194:197], v156 offset:2048
	ds_read_b128 v[198:201], v156 offset:3072
	ds_read_b128 v[202:205], v156 offset:4096
	ds_read_b128 v[206:209], v156 offset:5120
	ds_read_b128 v[210:213], v156 offset:6144
	ds_read_b128 v[214:217], v156 offset:7168
	global_load_lds_dwordx4 v[150:151], off
	v_lshl_add_u64 v[150:151], s[38:39], 0, v[140:141]
	s_add_i32 m0, s31, 0xe000
	s_nop 0
	global_load_lds_dwordx4 v[150:151], off
	s_waitcnt vmcnt(8)
	s_waitcnt lgkmcnt(0)
	s_barrier
	s_setprio 1
	s_waitcnt lgkmcnt(0)
	v_mfma_f32_16x16x32_bf16 v[126:129], v[146:149], v[186:189], v[126:129]
	v_mfma_f32_16x16x32_bf16 v[122:125], v[162:165], v[186:189], v[122:125]
	v_mfma_f32_16x16x32_bf16 v[110:113], v[146:149], v[194:197], v[110:113]
	v_mfma_f32_16x16x32_bf16 v[106:109], v[162:165], v[194:197], v[106:109]
	v_mfma_f32_16x16x32_bf16 v[94:97], v[146:149], v[202:205], v[94:97]
	v_mfma_f32_16x16x32_bf16 v[90:93], v[162:165], v[202:205], v[90:93]
	v_mfma_f32_16x16x32_bf16 v[78:81], v[146:149], v[210:213], v[78:81]
	v_mfma_f32_16x16x32_bf16 v[74:77], v[162:165], v[210:213], v[74:77]
	v_mfma_f32_16x16x32_bf16 v[126:129], v[158:161], v[190:193], v[126:129]
	v_mfma_f32_16x16x32_bf16 v[122:125], v[166:169], v[190:193], v[122:125]
	v_mfma_f32_16x16x32_bf16 v[110:113], v[158:161], v[198:201], v[110:113]
	v_mfma_f32_16x16x32_bf16 v[106:109], v[166:169], v[198:201], v[106:109]
	v_mfma_f32_16x16x32_bf16 v[94:97], v[158:161], v[206:209], v[94:97]
	v_mfma_f32_16x16x32_bf16 v[90:93], v[166:169], v[206:209], v[90:93]
	v_mfma_f32_16x16x32_bf16 v[78:81], v[158:161], v[214:217], v[78:81]
	v_mfma_f32_16x16x32_bf16 v[74:77], v[166:169], v[214:217], v[74:77]
	v_mfma_f32_16x16x32_bf16 v[118:121], v[170:173], v[186:189], v[118:121]
	v_mfma_f32_16x16x32_bf16 v[114:117], v[178:181], v[186:189], v[114:117]
	v_mfma_f32_16x16x32_bf16 v[102:105], v[170:173], v[194:197], v[102:105]
	v_mfma_f32_16x16x32_bf16 v[98:101], v[178:181], v[194:197], v[98:101]
	v_mfma_f32_16x16x32_bf16 v[86:89], v[170:173], v[202:205], v[86:89]
	v_mfma_f32_16x16x32_bf16 v[82:85], v[178:181], v[202:205], v[82:85]
	v_mfma_f32_16x16x32_bf16 v[70:73], v[170:173], v[210:213], v[70:73]
	v_mfma_f32_16x16x32_bf16 v[66:69], v[178:181], v[210:213], v[66:69]
	v_mfma_f32_16x16x32_bf16 v[118:121], v[174:177], v[190:193], v[118:121]
	v_mfma_f32_16x16x32_bf16 v[114:117], v[182:185], v[190:193], v[114:117]
	v_mfma_f32_16x16x32_bf16 v[102:105], v[174:177], v[198:201], v[102:105]
	v_mfma_f32_16x16x32_bf16 v[98:101], v[182:185], v[198:201], v[98:101]
	v_mfma_f32_16x16x32_bf16 v[86:89], v[174:177], v[206:209], v[86:89]
	v_mfma_f32_16x16x32_bf16 v[82:85], v[182:185], v[206:209], v[82:85]
	v_mfma_f32_16x16x32_bf16 v[70:73], v[174:177], v[214:217], v[70:73]
	v_mfma_f32_16x16x32_bf16 v[66:69], v[182:185], v[214:217], v[66:69]
	s_setprio 0
	s_barrier
	s_add_i32 s62, s57, s30
	v_lshl_add_u64 v[150:151], s[40:41], 0, v[132:133]
	s_mov_b32 m0, s62
	ds_read_b128 v[186:189], v156 offset:16384
	ds_read_b128 v[190:193], v156 offset:17408
	ds_read_b128 v[194:197], v156 offset:18432
	ds_read_b128 v[198:201], v156 offset:19456
	ds_read_b128 v[202:205], v156 offset:20480
	ds_read_b128 v[206:209], v156 offset:21504
	ds_read_b128 v[210:213], v156 offset:22528
	ds_read_b128 v[214:217], v156 offset:23552
	global_load_lds_dwordx4 v[150:151], off
	s_add_i32 m0, s62, 0x2000
	s_add_u32 s62, s40, 0x10000
	v_lshl_add_u64 v[218:219], s[40:41], 0, v[136:137]
	s_addc_u32 s63, s41, 0
	s_add_i32 s64, s58, s30
	global_load_lds_dwordx4 v[218:219], off
	v_lshl_add_u64 v[220:221], s[62:63], 0, v[132:133]
	s_mov_b32 m0, s64
	v_lshl_add_u64 v[222:223], s[42:43], 0, v[134:135]
	global_load_lds_dwordx4 v[220:221], off
	v_lshl_add_u64 v[220:221], s[62:63], 0, v[136:137]
	s_add_i32 m0, s64, 0x2000
	s_nop 0
	global_load_lds_dwordx4 v[220:221], off
	v_lshl_add_u64 v[220:221], s[42:43], 0, v[130:131]
	s_mov_b32 m0, s31
	s_nop 0
	global_load_lds_dwordx4 v[220:221], off
	s_mov_b32 m0, s33
	s_nop 0
	global_load_lds_dwordx4 v[222:223], off
	s_waitcnt vmcnt(8)
	s_waitcnt lgkmcnt(0)
	s_barrier
; #define PG8_STAGE(bufoff, gbase, voff) do { _Pragma("unroll") for (int _i = 0; _i < 2; ++_i) \
;         __builtin_amdgcn_global_load_lds((const unsigned*)((const char*)(gbase) + (voff)[_i]), (PG8_LAS unsigned*)(lds + (bufoff) + ldsw + _i * 8192), 16, 0, 0); } while (0)
; #define PG8_LDA(dst, b, h) do { _Pragma("unroll") for (int m = 0; m < 4; ++m) _Pragma("unroll") for (int k = 0; k < 2; ++k) dst[m][k] = *(const PG8_LAS bf16x8*)(lds + PG8_SA(b, h) + aoff + m * 2048 + k * 1024); } while (0)
; #define PG8_LDB(dst, b, h) do { _Pragma("unroll") for (int n = 0; n < 2; ++n) _Pragma("unroll") for (int k = 0; k < 2; ++k) dst[n][k] = *(const PG8_LAS bf16x8*)(lds + PG8_SB(b, h) + boff + n * 2048 + k * 1024); } while (0)
; #define PG8_MMA(ai, bj, At, Bt) do { __builtin_amdgcn_s_setprio(1); _Pragma("unroll") for (int m = 0; m < 4; ++m) _Pragma("unroll") for (int n = 0; n < 2; ++n) _Pragma("unroll") for (int k = 0; k < 2; ++k) \
;         acc[ai][bj][m][n] = __builtin_amdgcn_mfma_f32_16x16x32_bf16(Bt[n][k], At[m][k], acc[ai][bj][m][n], 0, 0, 0); __builtin_amdgcn_s_setprio(0); } while (0)
; #define PG8_WAIT_V(n) asm volatile("s_waitcnt vmcnt(" #n ")" ::: "memory")
; #define PG8_WAIT_L(n) asm volatile("s_waitcnt lgkmcnt(" #n ")" ::: "memory")
; #define PG8_BAR __builtin_amdgcn_s_barrier()
; #define PG8_SCHED __builtin_amdgcn_sched_barrier(0)
; template <class Epi, class Sched, bool ALIGN_EPI = false, bool SP2 = false>
; __device__ __forceinline__ void gemm_phase(PG8_LAS unsigned char* lds, const Gemm g, const Sched& S, const Epi& E) {
;     ...
;             PG8_WAIT_V(8); PG8_WAIT_L(0); PG8_BAR; PG8_MMA(1, 0, At, B0); PG8_MMA(1, 1, At, B1); PG8_BAR; PG8_SCHED;
;             PG8_LDB(B0, 1, 0); PG8_LDB(B1, 1, 1); PG8_SCHED; PG8_LDA(At, 1, 0); PG8_STAGE(PG8_SA(0, 1), a2 + hstep, voffA);
;             PG8_WAIT_V(8); PG8_WAIT_L(0); PG8_BAR; PG8_MMA(0, 0, At, B0); PG8_MMA(0, 1, At, B1); PG8_BAR; PG8_SCHED;
	s_setprio 1
	s_waitcnt lgkmcnt(0)
	v_mfma_f32_16x16x32_bf16 v[62:65], v[146:149], v[186:189], v[62:65]
	v_mfma_f32_16x16x32_bf16 v[58:61], v[162:165], v[186:189], v[58:61]
	v_mfma_f32_16x16x32_bf16 v[46:49], v[146:149], v[194:197], v[46:49]
	v_mfma_f32_16x16x32_bf16 v[42:45], v[162:165], v[194:197], v[42:45]
	v_mfma_f32_16x16x32_bf16 v[30:33], v[146:149], v[202:205], v[30:33]
	v_mfma_f32_16x16x32_bf16 v[26:29], v[162:165], v[202:205], v[26:29]
	v_mfma_f32_16x16x32_bf16 v[14:17], v[146:149], v[210:213], v[14:17]
	v_mfma_f32_16x16x32_bf16 v[10:13], v[162:165], v[210:213], v[10:13]
	v_mfma_f32_16x16x32_bf16 v[62:65], v[158:161], v[190:193], v[62:65]
	v_mfma_f32_16x16x32_bf16 v[58:61], v[166:169], v[190:193], v[58:61]
	v_mfma_f32_16x16x32_bf16 v[46:49], v[158:161], v[198:201], v[46:49]
	v_mfma_f32_16x16x32_bf16 v[42:45], v[166:169], v[198:201], v[42:45]
	v_mfma_f32_16x16x32_bf16 v[30:33], v[158:161], v[206:209], v[30:33]
	v_mfma_f32_16x16x32_bf16 v[26:29], v[166:169], v[206:209], v[26:29]
	v_mfma_f32_16x16x32_bf16 v[14:17], v[158:161], v[214:217], v[14:17]
	v_mfma_f32_16x16x32_bf16 v[10:13], v[166:169], v[214:217], v[10:13]
	v_mfma_f32_16x16x32_bf16 v[54:57], v[170:173], v[186:189], v[54:57]
	v_mfma_f32_16x16x32_bf16 v[50:53], v[178:181], v[186:189], v[50:53]
	v_mfma_f32_16x16x32_bf16 v[38:41], v[170:173], v[194:197], v[38:41]
	v_mfma_f32_16x16x32_bf16 v[34:37], v[178:181], v[194:197], v[34:37]
	v_mfma_f32_16x16x32_bf16 v[22:25], v[170:173], v[202:205], v[22:25]
	v_mfma_f32_16x16x32_bf16 v[18:21], v[178:181], v[202:205], v[18:21]
	v_mfma_f32_16x16x32_bf16 v[6:9], v[170:173], v[210:213], v[6:9]
	v_mfma_f32_16x16x32_bf16 v[2:5], v[178:181], v[210:213], v[2:5]
	v_mfma_f32_16x16x32_bf16 v[54:57], v[174:177], v[190:193], v[54:57]
	v_mfma_f32_16x16x32_bf16 v[50:53], v[182:185], v[190:193], v[50:53]
	v_mfma_f32_16x16x32_bf16 v[38:41], v[174:177], v[198:201], v[38:41]
	v_mfma_f32_16x16x32_bf16 v[34:37], v[182:185], v[198:201], v[34:37]
	v_mfma_f32_16x16x32_bf16 v[22:25], v[174:177], v[206:209], v[22:25]
	v_mfma_f32_16x16x32_bf16 v[18:21], v[182:185], v[206:209], v[18:21]
	v_mfma_f32_16x16x32_bf16 v[6:9], v[174:177], v[214:217], v[6:9]
	v_mfma_f32_16x16x32_bf16 v[2:5], v[182:185], v[214:217], v[2:5]
	s_setprio 0
	s_barrier
	s_add_i32 s62, 0, 0x18000
	v_add_u32_e32 v157, s62, v152
	s_add_i32 s63, 0, 0x1c000
	ds_read_b128 v[146:149], v157
	ds_read_b128 v[158:161], v157 offset:1024
	ds_read_b128 v[162:165], v157 offset:2048
	ds_read_b128 v[166:169], v157 offset:3072
	v_add_u32_e32 v157, s63, v152
	ds_read_b128 v[170:173], v157
	ds_read_b128 v[174:177], v157 offset:1024
	ds_read_b128 v[178:181], v157 offset:2048
	ds_read_b128 v[182:185], v157 offset:3072
	s_add_u32 s42, s42, 0x40000
	s_addc_u32 s43, s43, 0
	s_mov_b32 m0, s44
	v_lshl_add_u64 v[224:225], s[42:43], 0, v[130:131]
	ds_read_b128 v[186:189], v156 offset:32768
	ds_read_b128 v[190:193], v156 offset:33792
	ds_read_b128 v[194:197], v156 offset:34816
	ds_read_b128 v[198:201], v156 offset:35840
	ds_read_b128 v[202:205], v156 offset:36864
	ds_read_b128 v[206:209], v156 offset:37888
	ds_read_b128 v[210:213], v156 offset:38912
	ds_read_b128 v[214:217], v156 offset:39936
	global_load_lds_dwordx4 v[224:225], off
	v_lshl_add_u64 v[224:225], s[42:43], 0, v[134:135]
	s_mov_b32 m0, s45
	s_nop 0
	global_load_lds_dwordx4 v[224:225], off
	s_waitcnt vmcnt(8)
	s_waitcnt lgkmcnt(0)
	s_barrier
	s_setprio 1
	s_waitcnt lgkmcnt(0)
	v_mfma_f32_16x16x32_bf16 v[126:129], v[146:149], v[186:189], v[126:129]
	v_mfma_f32_16x16x32_bf16 v[122:125], v[162:165], v[186:189], v[122:125]
	v_mfma_f32_16x16x32_bf16 v[110:113], v[146:149], v[194:197], v[110:113]
	v_mfma_f32_16x16x32_bf16 v[106:109], v[162:165], v[194:197], v[106:109]
	v_mfma_f32_16x16x32_bf16 v[94:97], v[146:149], v[202:205], v[94:97]
	v_mfma_f32_16x16x32_bf16 v[90:93], v[162:165], v[202:205], v[90:93]
	v_mfma_f32_16x16x32_bf16 v[78:81], v[146:149], v[210:213], v[78:81]
	v_mfma_f32_16x16x32_bf16 v[74:77], v[162:165], v[210:213], v[74:77]
	v_mfma_f32_16x16x32_bf16 v[126:129], v[158:161], v[190:193], v[126:129]
	v_mfma_f32_16x16x32_bf16 v[122:125], v[166:169], v[190:193], v[122:125]
	v_mfma_f32_16x16x32_bf16 v[110:113], v[158:161], v[198:201], v[110:113]
	v_mfma_f32_16x16x32_bf16 v[106:109], v[166:169], v[198:201], v[106:109]
	v_mfma_f32_16x16x32_bf16 v[94:97], v[158:161], v[206:209], v[94:97]
	v_mfma_f32_16x16x32_bf16 v[90:93], v[166:169], v[206:209], v[90:93]
	v_mfma_f32_16x16x32_bf16 v[78:81], v[158:161], v[214:217], v[78:81]
	v_mfma_f32_16x16x32_bf16 v[74:77], v[166:169], v[214:217], v[74:77]
	v_mfma_f32_16x16x32_bf16 v[118:121], v[170:173], v[186:189], v[118:121]
	v_mfma_f32_16x16x32_bf16 v[114:117], v[178:181], v[186:189], v[114:117]
	v_mfma_f32_16x16x32_bf16 v[102:105], v[170:173], v[194:197], v[102:105]
	v_mfma_f32_16x16x32_bf16 v[98:101], v[178:181], v[194:197], v[98:101]
	v_mfma_f32_16x16x32_bf16 v[86:89], v[170:173], v[202:205], v[86:89]
	v_mfma_f32_16x16x32_bf16 v[82:85], v[178:181], v[202:205], v[82:85]
	v_mfma_f32_16x16x32_bf16 v[70:73], v[170:173], v[210:213], v[70:73]
	v_mfma_f32_16x16x32_bf16 v[66:69], v[178:181], v[210:213], v[66:69]
	v_mfma_f32_16x16x32_bf16 v[118:121], v[174:177], v[190:193], v[118:121]
	v_mfma_f32_16x16x32_bf16 v[114:117], v[182:185], v[190:193], v[114:117]
	v_mfma_f32_16x16x32_bf16 v[102:105], v[174:177], v[198:201], v[102:105]
	v_mfma_f32_16x16x32_bf16 v[98:101], v[182:185], v[198:201], v[98:101]
	v_mfma_f32_16x16x32_bf16 v[86:89], v[174:177], v[206:209], v[86:89]
	v_mfma_f32_16x16x32_bf16 v[82:85], v[182:185], v[206:209], v[82:85]
	v_mfma_f32_16x16x32_bf16 v[70:73], v[174:177], v[214:217], v[70:73]
	v_mfma_f32_16x16x32_bf16 v[66:69], v[182:185], v[214:217], v[66:69]
	s_setprio 0
	s_barrier
; #define PG8_STAGE(bufoff, gbase, voff) do { _Pragma("unroll") for (int _i = 0; _i < 2; ++_i) \
;         __builtin_amdgcn_global_load_lds((const unsigned*)((const char*)(gbase) + (voff)[_i]), (PG8_LAS unsigned*)(lds + (bufoff) + ldsw + _i * 8192), 16, 0, 0); } while (0)
; #define PG8_LDA(dst, b, h) do { _Pragma("unroll") for (int m = 0; m < 4; ++m) _Pragma("unroll") for (int k = 0; k < 2; ++k) dst[m][k] = *(const PG8_LAS bf16x8*)(lds + PG8_SA(b, h) + aoff + m * 2048 + k * 1024); } while (0)
; #define PG8_MMA(ai, bj, At, Bt) do { __builtin_amdgcn_s_setprio(1); _Pragma("unroll") for (int m = 0; m < 4; ++m) _Pragma("unroll") for (int n = 0; n < 2; ++n) _Pragma("unroll") for (int k = 0; k < 2; ++k) \
;         acc[ai][bj][m][n] = __builtin_amdgcn_mfma_f32_16x16x32_bf16(Bt[n][k], At[m][k], acc[ai][bj][m][n], 0, 0, 0); __builtin_amdgcn_s_setprio(0); } while (0)
; #define PG8_WAIT_V(n) asm volatile("s_waitcnt vmcnt(" #n ")" ::: "memory")
; #define PG8_WAIT_L(n) asm volatile("s_waitcnt lgkmcnt(" #n ")" ::: "memory")
; #define PG8_BAR __builtin_amdgcn_s_barrier()
; #define PG8_SCHED __builtin_amdgcn_sched_barrier(0)
; template <class Epi, class Sched, bool ALIGN_EPI = false, bool SP2 = false>
; __device__ __forceinline__ void gemm_phase(PG8_LAS unsigned char* lds, const Gemm g, const Sched& S, const Epi& E) {
;     ...
;             PG8_LDA(At, 1, 1); PG8_STAGE(PG8_SB(1, 0), b3, voffB); PG8_STAGE(PG8_SB(1, 1), b3 + hstepB, voffB); PG8_STAGE(PG8_SA(1, 0), a3, voffA);
;             PG8_WAIT_V(8); PG8_WAIT_L(0); PG8_BAR; PG8_MMA(1, 0, At, B0); PG8_MMA(1, 1, At, B1); PG8_BAR; PG8_SCHED;
;     ...
;         if constexpr (ALIGN_EPI) { if (wr == 0) PG8_BAR; }
	s_add_i32 s42, s62, s30
	v_lshl_add_u64 v[150:151], v[150:151], 0, s[10:11]
	s_mov_b32 m0, s42
	ds_read_b128 v[186:189], v156 offset:49152
	ds_read_b128 v[190:193], v156 offset:50176
	ds_read_b128 v[194:197], v156 offset:51200
	ds_read_b128 v[198:201], v156 offset:52224
	ds_read_b128 v[202:205], v156 offset:53248
	ds_read_b128 v[206:209], v156 offset:54272
	ds_read_b128 v[210:213], v156 offset:55296
	ds_read_b128 v[214:217], v156 offset:56320
	global_load_lds_dwordx4 v[150:151], off
	s_add_i32 m0, s42, 0x2000
	s_add_u32 s40, s40, 0x10080
	v_lshl_add_u64 v[150:151], v[218:219], 0, s[10:11]
	s_addc_u32 s41, s41, 0
	s_add_i32 s42, s63, s30
	global_load_lds_dwordx4 v[150:151], off
	v_lshl_add_u64 v[150:151], s[40:41], 0, v[132:133]
	s_mov_b32 m0, s42
	s_nop 0
	global_load_lds_dwordx4 v[150:151], off
	v_lshl_add_u64 v[150:151], s[40:41], 0, v[136:137]
	s_add_i32 m0, s42, 0x2000
	s_nop 0
	global_load_lds_dwordx4 v[150:151], off
	v_lshl_add_u64 v[150:151], v[220:221], 0, s[10:11]
	s_mov_b32 m0, s47
	s_nop 0
	global_load_lds_dwordx4 v[150:151], off
	v_lshl_add_u64 v[150:151], v[222:223], 0, s[10:11]
	s_mov_b32 m0, s54
	s_nop 0
	global_load_lds_dwordx4 v[150:151], off
	s_waitcnt vmcnt(8)
	s_waitcnt lgkmcnt(0)
	s_barrier
	s_setprio 1
	s_waitcnt lgkmcnt(0)
	v_mfma_f32_16x16x32_bf16 v[62:65], v[146:149], v[186:189], v[62:65]
	v_mfma_f32_16x16x32_bf16 v[58:61], v[162:165], v[186:189], v[58:61]
	v_mfma_f32_16x16x32_bf16 v[46:49], v[146:149], v[194:197], v[46:49]
	v_mfma_f32_16x16x32_bf16 v[42:45], v[162:165], v[194:197], v[42:45]
	v_mfma_f32_16x16x32_bf16 v[30:33], v[146:149], v[202:205], v[30:33]
	v_mfma_f32_16x16x32_bf16 v[26:29], v[162:165], v[202:205], v[26:29]
	v_mfma_f32_16x16x32_bf16 v[14:17], v[146:149], v[210:213], v[14:17]
	v_mfma_f32_16x16x32_bf16 v[10:13], v[162:165], v[210:213], v[10:13]
	v_mfma_f32_16x16x32_bf16 v[62:65], v[158:161], v[190:193], v[62:65]
	v_mfma_f32_16x16x32_bf16 v[58:61], v[166:169], v[190:193], v[58:61]
	v_mfma_f32_16x16x32_bf16 v[46:49], v[158:161], v[198:201], v[46:49]
	v_mfma_f32_16x16x32_bf16 v[42:45], v[166:169], v[198:201], v[42:45]
	v_mfma_f32_16x16x32_bf16 v[30:33], v[158:161], v[206:209], v[30:33]
	v_mfma_f32_16x16x32_bf16 v[26:29], v[166:169], v[206:209], v[26:29]
	v_mfma_f32_16x16x32_bf16 v[14:17], v[158:161], v[214:217], v[14:17]
	v_mfma_f32_16x16x32_bf16 v[10:13], v[166:169], v[214:217], v[10:13]
	v_mfma_f32_16x16x32_bf16 v[54:57], v[170:173], v[186:189], v[54:57]
	v_mfma_f32_16x16x32_bf16 v[50:53], v[178:181], v[186:189], v[50:53]
	v_mfma_f32_16x16x32_bf16 v[38:41], v[170:173], v[194:197], v[38:41]
	v_mfma_f32_16x16x32_bf16 v[34:37], v[178:181], v[194:197], v[34:37]
	v_mfma_f32_16x16x32_bf16 v[22:25], v[170:173], v[202:205], v[22:25]
	v_mfma_f32_16x16x32_bf16 v[18:21], v[178:181], v[202:205], v[18:21]
	v_mfma_f32_16x16x32_bf16 v[6:9], v[170:173], v[210:213], v[6:9]
	v_mfma_f32_16x16x32_bf16 v[2:5], v[178:181], v[210:213], v[2:5]
	v_mfma_f32_16x16x32_bf16 v[54:57], v[174:177], v[190:193], v[54:57]
	v_mfma_f32_16x16x32_bf16 v[50:53], v[182:185], v[190:193], v[50:53]
	v_mfma_f32_16x16x32_bf16 v[38:41], v[174:177], v[198:201], v[38:41]
	v_mfma_f32_16x16x32_bf16 v[34:37], v[182:185], v[198:201], v[34:37]
	v_mfma_f32_16x16x32_bf16 v[22:25], v[174:177], v[206:209], v[22:25]
	v_mfma_f32_16x16x32_bf16 v[18:21], v[182:185], v[206:209], v[18:21]
	v_mfma_f32_16x16x32_bf16 v[6:9], v[174:177], v[214:217], v[6:9]
	v_mfma_f32_16x16x32_bf16 v[2:5], v[182:185], v[214:217], v[2:5]
	s_setprio 0
	s_barrier
	s_add_i32 s61, s61, 2
	s_add_u32 s38, s38, 0x100
	s_addc_u32 s39, s39, 0
	s_add_u32 s59, s59, 0x100
	s_addc_u32 s60, s60, 0
	s_cmp_gt_u32 s61, 13
	s_cbranch_scc0 .LBB0_1313
	s_and_b64 vcc, exec, s[14:15]
	s_cbranch_vccz .LBB0_1316
	s_barrier

; #define PG8_STAGE(bufoff, gbase, voff) do { _Pragma("unroll") for (int _i = 0; _i < 2; ++_i) \
;         __builtin_amdgcn_global_load_lds((const unsigned*)((const char*)(gbase) + (voff)[_i]), (PG8_LAS unsigned*)(lds + (bufoff) + ldsw + _i * 8192), 16, 0, 0); } while (0)
; #define PG8_LDA(dst, b, h) do { _Pragma("unroll") for (int m = 0; m < 4; ++m) _Pragma("unroll") for (int k = 0; k < 2; ++k) dst[m][k] = *(const PG8_LAS bf16x8*)(lds + PG8_SA(b, h) + aoff + m * 2048 + k * 1024); } while (0)
; #define PG8_LDB(dst, b, h) do { _Pragma("unroll") for (int n = 0; n < 2; ++n) _Pragma("unroll") for (int k = 0; k < 2; ++k) dst[n][k] = *(const PG8_LAS bf16x8*)(lds + PG8_SB(b, h) + boff + n * 2048 + k * 1024); } while (0)
; #define PG8_MMA(ai, bj, At, Bt) do { __builtin_amdgcn_s_setprio(1); _Pragma("unroll") for (int m = 0; m < 4; ++m) _Pragma("unroll") for (int n = 0; n < 2; ++n) _Pragma("unroll") for (int k = 0; k < 2; ++k) \
;         acc[ai][bj][m][n] = __builtin_amdgcn_mfma_f32_16x16x32_bf16(Bt[n][k], At[m][k], acc[ai][bj][m][n], 0, 0, 0); __builtin_amdgcn_s_setprio(0); } while (0)
; #define PG8_WAIT_V(n) asm volatile("s_waitcnt vmcnt(" #n ")" ::: "memory")
; #define PG8_WAIT_L(n) asm volatile("s_waitcnt lgkmcnt(" #n ")" ::: "memory")
; #define PG8_BAR __builtin_amdgcn_s_barrier()
; #define PG8_SCHED __builtin_amdgcn_sched_barrier(0)
; template <class Epi, class Sched, bool ALIGN_EPI = false, bool SP2 = false>
; __device__ __forceinline__ void gemm_phase(PG8_LAS unsigned char* lds, const Gemm g, const Sched& S, const Epi& E) {
;     ...
;             PG8_LDB(B0, 0, 0); PG8_LDB(B1, 0, 1); PG8_SCHED; PG8_LDA(At, 0, 0); PG8_STAGE(PG8_SA(1, 1), a1 + hstep, voffA);
;             PG8_WAIT_V(8); PG8_WAIT_L(0); PG8_BAR; PG8_MMA(0, 0, At, B0); PG8_MMA(0, 1, At, B1); PG8_BAR; PG8_SCHED;
;             PG8_LDA(At, 0, 1); PG8_STAGE(PG8_SB(0, 0), b2, voffB); PG8_STAGE(PG8_SB(0, 1), b2 + hstepB, voffB); PG8_STAGE(PG8_SA(0, 0), a2, voffA);
.LBB0_1429:
	v_add_u32_e32 v164, s43, v150
	v_add_u32_e32 v180, s44, v150
	s_add_u32 s26, s8, s24
	ds_read_b128 v[152:155], v164
	ds_read_b128 v[156:159], v164 offset:1024
	ds_read_b128 v[160:163], v164 offset:2048
	ds_read_b128 v[164:167], v164 offset:3072
	ds_read_b128 v[168:171], v180
	ds_read_b128 v[172:175], v180 offset:1024
	ds_read_b128 v[176:179], v180 offset:2048
	ds_read_b128 v[180:183], v180 offset:3072
	s_addc_u32 s27, s9, s25
	s_add_u32 s26, s26, 0x100
	s_addc_u32 s27, s27, 0
	s_add_u32 s55, s21, s24
	s_addc_u32 s56, s45, s25
	s_cmpk_eq_i32 s24, 0x1f00
	s_cselect_b32 s29, s17, s27
	s_cselect_b32 s28, s46, s26
	s_cselect_b32 s27, s15, s56
	s_cselect_b32 s26, s47, s55
	v_lshl_add_u64 v[212:213], v[146:147], 0, s[24:25]
	s_add_i32 m0, s35, 0xc000
	ds_read_b128 v[184:187], v151
	ds_read_b128 v[188:191], v151 offset:1024
	ds_read_b128 v[192:195], v151 offset:2048
	ds_read_b128 v[196:199], v151 offset:3072
	ds_read_b128 v[200:203], v151 offset:4096
	ds_read_b128 v[204:207], v151 offset:5120
	ds_read_b128 v[208:211], v151 offset:6144
	ds_read_b128 v[218:221], v151 offset:7168
	global_load_lds_dwordx4 v[212:213], off
	v_lshl_add_u64 v[212:213], v[148:149], 0, s[24:25]
	s_add_i32 m0, s35, 0xe000
	s_nop 0
	global_load_lds_dwordx4 v[212:213], off
	s_waitcnt vmcnt(8)
	s_waitcnt lgkmcnt(0)
	s_barrier
	s_setprio 1
	s_waitcnt lgkmcnt(0)
	v_mfma_f32_16x16x32_bf16 v[126:129], v[152:155], v[184:187], v[126:129]
	v_mfma_f32_16x16x32_bf16 v[122:125], v[160:163], v[184:187], v[122:125]
	v_mfma_f32_16x16x32_bf16 v[110:113], v[152:155], v[192:195], v[110:113]
	v_mfma_f32_16x16x32_bf16 v[106:109], v[160:163], v[192:195], v[106:109]
	v_mfma_f32_16x16x32_bf16 v[94:97], v[152:155], v[200:203], v[94:97]
	v_mfma_f32_16x16x32_bf16 v[90:93], v[160:163], v[200:203], v[90:93]
	v_mfma_f32_16x16x32_bf16 v[78:81], v[152:155], v[208:211], v[78:81]
	v_mfma_f32_16x16x32_bf16 v[74:77], v[160:163], v[208:211], v[74:77]
	v_mfma_f32_16x16x32_bf16 v[126:129], v[156:159], v[188:191], v[126:129]
	v_mfma_f32_16x16x32_bf16 v[122:125], v[164:167], v[188:191], v[122:125]
	v_mfma_f32_16x16x32_bf16 v[110:113], v[156:159], v[196:199], v[110:113]
	v_mfma_f32_16x16x32_bf16 v[106:109], v[164:167], v[196:199], v[106:109]
	v_mfma_f32_16x16x32_bf16 v[94:97], v[156:159], v[204:207], v[94:97]
	v_mfma_f32_16x16x32_bf16 v[90:93], v[164:167], v[204:207], v[90:93]
	v_mfma_f32_16x16x32_bf16 v[78:81], v[156:159], v[218:221], v[78:81]
	v_mfma_f32_16x16x32_bf16 v[74:77], v[164:167], v[218:221], v[74:77]
	v_mfma_f32_16x16x32_bf16 v[118:121], v[168:171], v[184:187], v[118:121]
	v_mfma_f32_16x16x32_bf16 v[114:117], v[176:179], v[184:187], v[114:117]
	v_mfma_f32_16x16x32_bf16 v[102:105], v[168:171], v[192:195], v[102:105]
	v_mfma_f32_16x16x32_bf16 v[98:101], v[176:179], v[192:195], v[98:101]
	v_mfma_f32_16x16x32_bf16 v[86:89], v[168:171], v[200:203], v[86:89]
	v_mfma_f32_16x16x32_bf16 v[82:85], v[176:179], v[200:203], v[82:85]
	v_mfma_f32_16x16x32_bf16 v[70:73], v[168:171], v[208:211], v[70:73]
	v_mfma_f32_16x16x32_bf16 v[66:69], v[176:179], v[208:211], v[66:69]
	v_mfma_f32_16x16x32_bf16 v[118:121], v[172:175], v[188:191], v[118:121]
	v_mfma_f32_16x16x32_bf16 v[114:117], v[180:183], v[188:191], v[114:117]
	v_mfma_f32_16x16x32_bf16 v[102:105], v[172:175], v[196:199], v[102:105]
	v_mfma_f32_16x16x32_bf16 v[98:101], v[180:183], v[196:199], v[98:101]
	v_mfma_f32_16x16x32_bf16 v[86:89], v[172:175], v[204:207], v[86:89]
	v_mfma_f32_16x16x32_bf16 v[82:85], v[180:183], v[204:207], v[82:85]
	v_mfma_f32_16x16x32_bf16 v[70:73], v[172:175], v[218:221], v[70:73]
	v_mfma_f32_16x16x32_bf16 v[66:69], v[180:183], v[218:221], v[66:69]
	s_setprio 0
	s_barrier
	s_add_i32 s55, s43, s34
	v_lshl_add_u64 v[212:213], s[26:27], 0, v[132:133]
	s_mov_b32 m0, s55
	ds_read_b128 v[184:187], v151 offset:16384
	ds_read_b128 v[188:191], v151 offset:17408
	ds_read_b128 v[192:195], v151 offset:18432
	ds_read_b128 v[196:199], v151 offset:19456
	ds_read_b128 v[200:203], v151 offset:20480
	ds_read_b128 v[204:207], v151 offset:21504
	ds_read_b128 v[208:211], v151 offset:22528
	ds_read_b128 v[218:221], v151 offset:23552
	global_load_lds_dwordx4 v[212:213], off
	s_add_i32 m0, s55, 0x2000
	s_add_u32 s56, s26, 0x40000
	v_lshl_add_u64 v[222:223], s[26:27], 0, v[136:137]
	s_addc_u32 s57, s27, 0
	s_add_i32 s55, s44, s34
	global_load_lds_dwordx4 v[222:223], off
	v_lshl_add_u64 v[224:225], s[56:57], 0, v[132:133]
	s_mov_b32 m0, s55
	v_lshl_add_u64 v[226:227], s[28:29], 0, v[134:135]
	global_load_lds_dwordx4 v[224:225], off
	v_lshl_add_u64 v[224:225], s[56:57], 0, v[136:137]
	s_add_i32 m0, s55, 0x2000
	s_nop 0
	global_load_lds_dwordx4 v[224:225], off
	v_lshl_add_u64 v[224:225], s[28:29], 0, v[130:131]
	s_mov_b32 m0, s35
	s_nop 0
	global_load_lds_dwordx4 v[224:225], off
	s_mov_b32 m0, s36
	s_nop 0
	global_load_lds_dwordx4 v[226:227], off
	s_waitcnt vmcnt(8)
	s_waitcnt lgkmcnt(0)
	s_barrier
; #define PG8_STAGE(bufoff, gbase, voff) do { _Pragma("unroll") for (int _i = 0; _i < 2; ++_i) \
;         __builtin_amdgcn_global_load_lds((const unsigned*)((const char*)(gbase) + (voff)[_i]), (PG8_LAS unsigned*)(lds + (bufoff) + ldsw + _i * 8192), 16, 0, 0); } while (0)
; #define PG8_LDA(dst, b, h) do { _Pragma("unroll") for (int m = 0; m < 4; ++m) _Pragma("unroll") for (int k = 0; k < 2; ++k) dst[m][k] = *(const PG8_LAS bf16x8*)(lds + PG8_SA(b, h) + aoff + m * 2048 + k * 1024); } while (0)
; #define PG8_LDB(dst, b, h) do { _Pragma("unroll") for (int n = 0; n < 2; ++n) _Pragma("unroll") for (int k = 0; k < 2; ++k) dst[n][k] = *(const PG8_LAS bf16x8*)(lds + PG8_SB(b, h) + boff + n * 2048 + k * 1024); } while (0)
; #define PG8_MMA(ai, bj, At, Bt) do { __builtin_amdgcn_s_setprio(1); _Pragma("unroll") for (int m = 0; m < 4; ++m) _Pragma("unroll") for (int n = 0; n < 2; ++n) _Pragma("unroll") for (int k = 0; k < 2; ++k) \
;         acc[ai][bj][m][n] = __builtin_amdgcn_mfma_f32_16x16x32_bf16(Bt[n][k], At[m][k], acc[ai][bj][m][n], 0, 0, 0); __builtin_amdgcn_s_setprio(0); } while (0)
; #define PG8_WAIT_V(n) asm volatile("s_waitcnt vmcnt(" #n ")" ::: "memory")
; #define PG8_WAIT_L(n) asm volatile("s_waitcnt lgkmcnt(" #n ")" ::: "memory")
; #define PG8_BAR __builtin_amdgcn_s_barrier()
; #define PG8_SCHED __builtin_amdgcn_sched_barrier(0)
; template <class Epi, class Sched, bool ALIGN_EPI = false, bool SP2 = false>
; __device__ __forceinline__ void gemm_phase(PG8_LAS unsigned char* lds, const Gemm g, const Sched& S, const Epi& E) {
;     ...
;             PG8_WAIT_V(8); PG8_WAIT_L(0); PG8_BAR; PG8_MMA(1, 0, At, B0); PG8_MMA(1, 1, At, B1); PG8_BAR; PG8_SCHED;
;             PG8_LDB(B0, 1, 0); PG8_LDB(B1, 1, 1); PG8_SCHED; PG8_LDA(At, 1, 0); PG8_STAGE(PG8_SA(0, 1), a2 + hstep, voffA);
;             PG8_WAIT_V(8); PG8_WAIT_L(0); PG8_BAR; PG8_MMA(0, 0, At, B0); PG8_MMA(0, 1, At, B1); PG8_BAR; PG8_SCHED;
	s_setprio 1
	s_waitcnt lgkmcnt(0)
	v_mfma_f32_16x16x32_bf16 v[62:65], v[152:155], v[184:187], v[62:65]
	v_mfma_f32_16x16x32_bf16 v[58:61], v[160:163], v[184:187], v[58:61]
	v_mfma_f32_16x16x32_bf16 v[46:49], v[152:155], v[192:195], v[46:49]
	v_mfma_f32_16x16x32_bf16 v[42:45], v[160:163], v[192:195], v[42:45]
	v_mfma_f32_16x16x32_bf16 v[30:33], v[152:155], v[200:203], v[30:33]
	v_mfma_f32_16x16x32_bf16 v[26:29], v[160:163], v[200:203], v[26:29]
	v_mfma_f32_16x16x32_bf16 v[14:17], v[152:155], v[208:211], v[14:17]
	v_mfma_f32_16x16x32_bf16 v[10:13], v[160:163], v[208:211], v[10:13]
	v_mfma_f32_16x16x32_bf16 v[62:65], v[156:159], v[188:191], v[62:65]
	v_mfma_f32_16x16x32_bf16 v[58:61], v[164:167], v[188:191], v[58:61]
	v_mfma_f32_16x16x32_bf16 v[46:49], v[156:159], v[196:199], v[46:49]
	v_mfma_f32_16x16x32_bf16 v[42:45], v[164:167], v[196:199], v[42:45]
	v_mfma_f32_16x16x32_bf16 v[30:33], v[156:159], v[204:207], v[30:33]
	v_mfma_f32_16x16x32_bf16 v[26:29], v[164:167], v[204:207], v[26:29]
	v_mfma_f32_16x16x32_bf16 v[14:17], v[156:159], v[218:221], v[14:17]
	v_mfma_f32_16x16x32_bf16 v[10:13], v[164:167], v[218:221], v[10:13]
	v_mfma_f32_16x16x32_bf16 v[54:57], v[168:171], v[184:187], v[54:57]
	v_mfma_f32_16x16x32_bf16 v[50:53], v[176:179], v[184:187], v[50:53]
	v_mfma_f32_16x16x32_bf16 v[38:41], v[168:171], v[192:195], v[38:41]
	v_mfma_f32_16x16x32_bf16 v[34:37], v[176:179], v[192:195], v[34:37]
	v_mfma_f32_16x16x32_bf16 v[22:25], v[168:171], v[200:203], v[22:25]
	v_mfma_f32_16x16x32_bf16 v[18:21], v[176:179], v[200:203], v[18:21]
	v_mfma_f32_16x16x32_bf16 v[6:9], v[168:171], v[208:211], v[6:9]
	v_mfma_f32_16x16x32_bf16 v[2:5], v[176:179], v[208:211], v[2:5]
	v_mfma_f32_16x16x32_bf16 v[54:57], v[172:175], v[188:191], v[54:57]
	v_mfma_f32_16x16x32_bf16 v[50:53], v[180:183], v[188:191], v[50:53]
	v_mfma_f32_16x16x32_bf16 v[38:41], v[172:175], v[196:199], v[38:41]
	v_mfma_f32_16x16x32_bf16 v[34:37], v[180:183], v[196:199], v[34:37]
	v_mfma_f32_16x16x32_bf16 v[22:25], v[172:175], v[204:207], v[22:25]
	v_mfma_f32_16x16x32_bf16 v[18:21], v[180:183], v[204:207], v[18:21]
	v_mfma_f32_16x16x32_bf16 v[6:9], v[172:175], v[218:221], v[6:9]
	v_mfma_f32_16x16x32_bf16 v[2:5], v[180:183], v[218:221], v[2:5]
	s_setprio 0
	s_barrier
	s_add_i32 s55, 0, 0x18000
	s_add_i32 s56, 0, 0x1c000
	v_add_u32_e32 v164, s55, v150
	v_add_u32_e32 v180, s56, v150
	ds_read_b128 v[152:155], v164
	ds_read_b128 v[156:159], v164 offset:1024
	ds_read_b128 v[160:163], v164 offset:2048
	ds_read_b128 v[164:167], v164 offset:3072
	ds_read_b128 v[168:171], v180
	ds_read_b128 v[172:175], v180 offset:1024
	ds_read_b128 v[176:179], v180 offset:2048
	ds_read_b128 v[180:183], v180 offset:3072
	s_add_u32 s28, s28, 0x100000
	s_addc_u32 s29, s29, 0
	s_mov_b32 m0, s37
	v_lshl_add_u64 v[228:229], s[28:29], 0, v[130:131]
	ds_read_b128 v[184:187], v151 offset:32768
	ds_read_b128 v[188:191], v151 offset:33792
	ds_read_b128 v[192:195], v151 offset:34816
	ds_read_b128 v[196:199], v151 offset:35840
	ds_read_b128 v[200:203], v151 offset:36864
	ds_read_b128 v[204:207], v151 offset:37888
	ds_read_b128 v[208:211], v151 offset:38912
	ds_read_b128 v[218:221], v151 offset:39936
	global_load_lds_dwordx4 v[228:229], off
	v_lshl_add_u64 v[228:229], s[28:29], 0, v[134:135]
	s_mov_b32 m0, s39
	s_nop 0
	global_load_lds_dwordx4 v[228:229], off
	s_waitcnt vmcnt(8)
	s_waitcnt lgkmcnt(0)
	s_barrier
	s_setprio 1
	s_waitcnt lgkmcnt(0)
	v_mfma_f32_16x16x32_bf16 v[126:129], v[152:155], v[184:187], v[126:129]
	v_mfma_f32_16x16x32_bf16 v[122:125], v[160:163], v[184:187], v[122:125]
	v_mfma_f32_16x16x32_bf16 v[110:113], v[152:155], v[192:195], v[110:113]
	v_mfma_f32_16x16x32_bf16 v[106:109], v[160:163], v[192:195], v[106:109]
	v_mfma_f32_16x16x32_bf16 v[94:97], v[152:155], v[200:203], v[94:97]
	v_mfma_f32_16x16x32_bf16 v[90:93], v[160:163], v[200:203], v[90:93]
	v_mfma_f32_16x16x32_bf16 v[78:81], v[152:155], v[208:211], v[78:81]
	v_mfma_f32_16x16x32_bf16 v[74:77], v[160:163], v[208:211], v[74:77]
	v_mfma_f32_16x16x32_bf16 v[126:129], v[156:159], v[188:191], v[126:129]
	v_mfma_f32_16x16x32_bf16 v[122:125], v[164:167], v[188:191], v[122:125]
	v_mfma_f32_16x16x32_bf16 v[110:113], v[156:159], v[196:199], v[110:113]
	v_mfma_f32_16x16x32_bf16 v[106:109], v[164:167], v[196:199], v[106:109]
	v_mfma_f32_16x16x32_bf16 v[94:97], v[156:159], v[204:207], v[94:97]
	v_mfma_f32_16x16x32_bf16 v[90:93], v[164:167], v[204:207], v[90:93]
	v_mfma_f32_16x16x32_bf16 v[78:81], v[156:159], v[218:221], v[78:81]
	v_mfma_f32_16x16x32_bf16 v[74:77], v[164:167], v[218:221], v[74:77]
	v_mfma_f32_16x16x32_bf16 v[118:121], v[168:171], v[184:187], v[118:121]
	v_mfma_f32_16x16x32_bf16 v[114:117], v[176:179], v[184:187], v[114:117]
	v_mfma_f32_16x16x32_bf16 v[102:105], v[168:171], v[192:195], v[102:105]
	v_mfma_f32_16x16x32_bf16 v[98:101], v[176:179], v[192:195], v[98:101]
	v_mfma_f32_16x16x32_bf16 v[86:89], v[168:171], v[200:203], v[86:89]
	v_mfma_f32_16x16x32_bf16 v[82:85], v[176:179], v[200:203], v[82:85]
	v_mfma_f32_16x16x32_bf16 v[70:73], v[168:171], v[208:211], v[70:73]
	v_mfma_f32_16x16x32_bf16 v[66:69], v[176:179], v[208:211], v[66:69]
	v_mfma_f32_16x16x32_bf16 v[118:121], v[172:175], v[188:191], v[118:121]
	v_mfma_f32_16x16x32_bf16 v[114:117], v[180:183], v[188:191], v[114:117]
	v_mfma_f32_16x16x32_bf16 v[102:105], v[172:175], v[196:199], v[102:105]
	v_mfma_f32_16x16x32_bf16 v[98:101], v[180:183], v[196:199], v[98:101]
	v_mfma_f32_16x16x32_bf16 v[86:89], v[172:175], v[204:207], v[86:89]
	v_mfma_f32_16x16x32_bf16 v[82:85], v[180:183], v[204:207], v[82:85]
	v_mfma_f32_16x16x32_bf16 v[70:73], v[172:175], v[218:221], v[70:73]
	v_mfma_f32_16x16x32_bf16 v[66:69], v[180:183], v[218:221], v[66:69]
	s_setprio 0
	s_barrier
; #define PG8_STAGE(bufoff, gbase, voff) do { _Pragma("unroll") for (int _i = 0; _i < 2; ++_i) \
;         __builtin_amdgcn_global_load_lds((const unsigned*)((const char*)(gbase) + (voff)[_i]), (PG8_LAS unsigned*)(lds + (bufoff) + ldsw + _i * 8192), 16, 0, 0); } while (0)
; #define PG8_LDA(dst, b, h) do { _Pragma("unroll") for (int m = 0; m < 4; ++m) _Pragma("unroll") for (int k = 0; k < 2; ++k) dst[m][k] = *(const PG8_LAS bf16x8*)(lds + PG8_SA(b, h) + aoff + m * 2048 + k * 1024); } while (0)
; #define PG8_MMA(ai, bj, At, Bt) do { __builtin_amdgcn_s_setprio(1); _Pragma("unroll") for (int m = 0; m < 4; ++m) _Pragma("unroll") for (int n = 0; n < 2; ++n) _Pragma("unroll") for (int k = 0; k < 2; ++k) \
;         acc[ai][bj][m][n] = __builtin_amdgcn_mfma_f32_16x16x32_bf16(Bt[n][k], At[m][k], acc[ai][bj][m][n], 0, 0, 0); __builtin_amdgcn_s_setprio(0); } while (0)
; #define PG8_WAIT_V(n) asm volatile("s_waitcnt vmcnt(" #n ")" ::: "memory")
; #define PG8_WAIT_L(n) asm volatile("s_waitcnt lgkmcnt(" #n ")" ::: "memory")
; #define PG8_BAR __builtin_amdgcn_s_barrier()
; #define PG8_SCHED __builtin_amdgcn_sched_barrier(0)
; template <class Epi, class Sched, bool ALIGN_EPI = false, bool SP2 = false>
; __device__ __forceinline__ void gemm_phase(PG8_LAS unsigned char* lds, const Gemm g, const Sched& S, const Epi& E) {
;     ...
;             PG8_LDA(At, 1, 1); PG8_STAGE(PG8_SB(1, 0), b3, voffB); PG8_STAGE(PG8_SB(1, 1), b3 + hstepB, voffB); PG8_STAGE(PG8_SA(1, 0), a3, voffA);
;             PG8_WAIT_V(8); PG8_WAIT_L(0); PG8_BAR; PG8_MMA(1, 0, At, B0); PG8_MMA(1, 1, At, B1); PG8_BAR; PG8_SCHED;
;     ...
; #pragma unroll
;         for (int a = 0; a < 2; ++a)
; #pragma unroll
;             for (int b = 0; b < 2; ++b)
; #pragma unroll
;                 for (int m = 0; m < 4; ++m)
; #pragma unroll
;                     for (int n = 0; n < 2; ++n) acc[a][b][m][n] = (f32x4){0.f, 0.f, 0.f, 0.f};
;         cur = nxt; cA = nA; cB = nB; ++ui;
	s_add_i32 s28, s55, s34
	v_lshl_add_u64 v[212:213], v[212:213], 0, s[10:11]
	s_mov_b32 m0, s28
	ds_read_b128 v[184:187], v151 offset:49152
	ds_read_b128 v[188:191], v151 offset:50176
	ds_read_b128 v[192:195], v151 offset:51200
	ds_read_b128 v[196:199], v151 offset:52224
	ds_read_b128 v[200:203], v151 offset:53248
	ds_read_b128 v[204:207], v151 offset:54272
	ds_read_b128 v[208:211], v151 offset:55296
	ds_read_b128 v[218:221], v151 offset:56320
	global_load_lds_dwordx4 v[212:213], off
	s_add_i32 m0, s28, 0x2000
	s_add_u32 s26, s26, 0x40080
	v_lshl_add_u64 v[212:213], v[222:223], 0, s[10:11]
	s_addc_u32 s27, s27, 0
	s_add_i32 s28, s56, s34
	global_load_lds_dwordx4 v[212:213], off
	v_lshl_add_u64 v[212:213], s[26:27], 0, v[132:133]
	s_mov_b32 m0, s28
	s_nop 0
	global_load_lds_dwordx4 v[212:213], off
	v_lshl_add_u64 v[212:213], s[26:27], 0, v[136:137]
	s_add_i32 m0, s28, 0x2000
	s_nop 0
	global_load_lds_dwordx4 v[212:213], off
	v_lshl_add_u64 v[212:213], v[224:225], 0, s[10:11]
	s_mov_b32 m0, s40
	s_nop 0
	global_load_lds_dwordx4 v[212:213], off
	v_lshl_add_u64 v[212:213], v[226:227], 0, s[10:11]
	s_mov_b32 m0, s41
	s_nop 0
	global_load_lds_dwordx4 v[212:213], off
	s_waitcnt vmcnt(8)
	s_waitcnt lgkmcnt(0)
	s_barrier
	s_setprio 1
	s_waitcnt lgkmcnt(0)
	v_mfma_f32_16x16x32_bf16 v[62:65], v[152:155], v[184:187], v[62:65]
	v_mfma_f32_16x16x32_bf16 v[58:61], v[160:163], v[184:187], v[58:61]
	v_mfma_f32_16x16x32_bf16 v[46:49], v[152:155], v[192:195], v[46:49]
	v_mfma_f32_16x16x32_bf16 v[42:45], v[160:163], v[192:195], v[42:45]
	v_mfma_f32_16x16x32_bf16 v[30:33], v[152:155], v[200:203], v[30:33]
	v_mfma_f32_16x16x32_bf16 v[26:29], v[160:163], v[200:203], v[26:29]
	v_mfma_f32_16x16x32_bf16 v[14:17], v[152:155], v[208:211], v[14:17]
	v_mfma_f32_16x16x32_bf16 v[10:13], v[160:163], v[208:211], v[10:13]
	v_mfma_f32_16x16x32_bf16 v[62:65], v[156:159], v[188:191], v[62:65]
	v_mfma_f32_16x16x32_bf16 v[58:61], v[164:167], v[188:191], v[58:61]
	v_mfma_f32_16x16x32_bf16 v[46:49], v[156:159], v[196:199], v[46:49]
	v_mfma_f32_16x16x32_bf16 v[42:45], v[164:167], v[196:199], v[42:45]
	v_mfma_f32_16x16x32_bf16 v[30:33], v[156:159], v[204:207], v[30:33]
	v_mfma_f32_16x16x32_bf16 v[26:29], v[164:167], v[204:207], v[26:29]
	v_mfma_f32_16x16x32_bf16 v[14:17], v[156:159], v[218:221], v[14:17]
	v_mfma_f32_16x16x32_bf16 v[10:13], v[164:167], v[218:221], v[10:13]
	v_mfma_f32_16x16x32_bf16 v[54:57], v[168:171], v[184:187], v[54:57]
	v_mfma_f32_16x16x32_bf16 v[50:53], v[176:179], v[184:187], v[50:53]
	v_mfma_f32_16x16x32_bf16 v[38:41], v[168:171], v[192:195], v[38:41]
	v_mfma_f32_16x16x32_bf16 v[34:37], v[176:179], v[192:195], v[34:37]
	v_mfma_f32_16x16x32_bf16 v[22:25], v[168:171], v[200:203], v[22:25]
	v_mfma_f32_16x16x32_bf16 v[18:21], v[176:179], v[200:203], v[18:21]
	v_mfma_f32_16x16x32_bf16 v[6:9], v[168:171], v[208:211], v[6:9]
	v_mfma_f32_16x16x32_bf16 v[2:5], v[176:179], v[208:211], v[2:5]
	v_mfma_f32_16x16x32_bf16 v[54:57], v[172:175], v[188:191], v[54:57]
	v_mfma_f32_16x16x32_bf16 v[50:53], v[180:183], v[188:191], v[50:53]
	v_mfma_f32_16x16x32_bf16 v[38:41], v[172:175], v[196:199], v[38:41]
	v_mfma_f32_16x16x32_bf16 v[34:37], v[180:183], v[196:199], v[34:37]
	v_mfma_f32_16x16x32_bf16 v[22:25], v[172:175], v[204:207], v[22:25]
	v_mfma_f32_16x16x32_bf16 v[18:21], v[180:183], v[204:207], v[18:21]
	v_mfma_f32_16x16x32_bf16 v[6:9], v[172:175], v[218:221], v[6:9]
	v_mfma_f32_16x16x32_bf16 v[2:5], v[180:183], v[218:221], v[2:5]
	s_setprio 0
	s_barrier
	s_add_i32 s54, s54, 2
	s_add_u32 s24, s24, 0x100
	s_addc_u32 s25, s25, 0
	s_cmp_gt_u32 s54, 61
	s_cbranch_scc0 .LBB0_1429
	s_add_u32 s24, s21, 0xffffff00
	s_addc_u32 s25, s45, -1
	s_andn2_b64 vcc, exec, s[2:3]
	s_cbranch_vccnz .LBB0_1420
	v_mov_b32_e32 v2, 0
	s_mov_b32 s6, s14
	s_mov_b32 s4, s16
	s_mov_b64 s[8:9], s[22:23]
	s_mov_b32 s42, s20
	v_mov_b32_e32 v3, v2
	v_mov_b32_e32 v4, v2
	v_mov_b32_e32 v5, v2
	v_mov_b32_e32 v6, v2
	v_mov_b32_e32 v7, v2
	v_mov_b32_e32 v8, v2
	v_mov_b32_e32 v9, v2
	v_mov_b32_e32 v18, v2
	v_mov_b32_e32 v19, v2
	v_mov_b32_e32 v20, v2
	v_mov_b32_e32 v21, v2
	v_mov_b32_e32 v22, v2
	v_mov_b32_e32 v23, v2
	v_mov_b32_e32 v24, v2
	v_mov_b32_e32 v25, v2
	v_mov_b32_e32 v34, v2
	v_mov_b32_e32 v35, v2
	v_mov_b32_e32 v36, v2
	v_mov_b32_e32 v37, v2
	v_mov_b32_e32 v38, v2
	v_mov_b32_e32 v39, v2
	v_mov_b32_e32 v40, v2
	v_mov_b32_e32 v41, v2
	v_mov_b32_e32 v50, v2
	v_mov_b32_e32 v51, v2
	v_mov_b32_e32 v52, v2
	v_mov_b32_e32 v53, v2
	v_mov_b32_e32 v54, v2
	v_mov_b32_e32 v55, v2
	v_mov_b32_e32 v56, v2
	v_mov_b32_e32 v57, v2
	v_mov_b32_e32 v10, v2
	v_mov_b32_e32 v11, v2
	v_mov_b32_e32 v12, v2
	v_mov_b32_e32 v13, v2
	v_mov_b32_e32 v14, v2
	v_mov_b32_e32 v15, v2
	v_mov_b32_e32 v16, v2
	v_mov_b32_e32 v17, v2
	v_mov_b32_e32 v26, v2
	v_mov_b32_e32 v27, v2
	v_mov_b32_e32 v28, v2
	v_mov_b32_e32 v29, v2
	v_mov_b32_e32 v30, v2
	v_mov_b32_e32 v31, v2
	v_mov_b32_e32 v32, v2
	v_mov_b32_e32 v33, v2
	v_mov_b32_e32 v42, v2
	v_mov_b32_e32 v43, v2
	v_mov_b32_e32 v44, v2
	v_mov_b32_e32 v45, v2
	v_mov_b32_e32 v46, v2
	v_mov_b32_e32 v47, v2
	v_mov_b32_e32 v48, v2
	v_mov_b32_e32 v49, v2
	v_mov_b32_e32 v58, v2
	v_mov_b32_e32 v59, v2
	v_mov_b32_e32 v60, v2
	v_mov_b32_e32 v61, v2
	v_mov_b32_e32 v62, v2
	v_mov_b32_e32 v63, v2
	v_mov_b32_e32 v64, v2
	v_mov_b32_e32 v65, v2
	v_mov_b32_e32 v66, v2
	v_mov_b32_e32 v67, v2
	v_mov_b32_e32 v68, v2
	v_mov_b32_e32 v69, v2
	v_mov_b32_e32 v70, v2
	v_mov_b32_e32 v71, v2
	v_mov_b32_e32 v72, v2
	v_mov_b32_e32 v73, v2
	v_mov_b32_e32 v82, v2
	v_mov_b32_e32 v83, v2
	v_mov_b32_e32 v84, v2
	v_mov_b32_e32 v85, v2
	v_mov_b32_e32 v86, v2
	v_mov_b32_e32 v87, v2
	v_mov_b32_e32 v88, v2
	v_mov_b32_e32 v89, v2
	v_mov_b32_e32 v98, v2
	v_mov_b32_e32 v99, v2
	v_mov_b32_e32 v100, v2
	v_mov_b32_e32 v101, v2
	v_mov_b32_e32 v102, v2
	v_mov_b32_e32 v103, v2
	v_mov_b32_e32 v104, v2
	v_mov_b32_e32 v105, v2
	v_mov_b32_e32 v114, v2
	v_mov_b32_e32 v115, v2
	v_mov_b32_e32 v116, v2
	v_mov_b32_e32 v117, v2
	v_mov_b32_e32 v118, v2
	v_mov_b32_e32 v119, v2
	v_mov_b32_e32 v120, v2
	v_mov_b32_e32 v121, v2
	v_mov_b32_e32 v74, v2
	v_mov_b32_e32 v75, v2
	v_mov_b32_e32 v76, v2
	v_mov_b32_e32 v77, v2
	v_mov_b32_e32 v78, v2
	v_mov_b32_e32 v79, v2
	v_mov_b32_e32 v80, v2
	v_mov_b32_e32 v81, v2
	v_mov_b32_e32 v90, v2
	v_mov_b32_e32 v91, v2
	v_mov_b32_e32 v92, v2
	v_mov_b32_e32 v93, v2
	v_mov_b32_e32 v94, v2
	v_mov_b32_e32 v95, v2
	v_mov_b32_e32 v96, v2
	v_mov_b32_e32 v97, v2
	v_mov_b32_e32 v106, v2
	v_mov_b32_e32 v107, v2
	v_mov_b32_e32 v108, v2
	v_mov_b32_e32 v109, v2
	v_mov_b32_e32 v110, v2
	v_mov_b32_e32 v111, v2
	v_mov_b32_e32 v112, v2
	v_mov_b32_e32 v113, v2
	v_mov_b32_e32 v122, v2
	v_mov_b32_e32 v123, v2
	v_mov_b32_e32 v124, v2
	v_mov_b32_e32 v125, v2
	v_mov_b32_e32 v126, v2
	v_mov_b32_e32 v127, v2
	v_mov_b32_e32 v128, v2
	v_mov_b32_e32 v129, v2
	s_andn2_b64 vcc, exec, s[0:1]
	s_cbranch_vccnz .LBB0_1421
